# adds: QKV v-section fast path (skips norm math multiplied by 1.0), incremental store addresses + arithmetic partner address in QKV epilogue, incremental addresses in UP/MIN epilogue
# baseline (speedup 1.0000x reference)
; __device__ __forceinline__ unsigned cvt_pk_bf16(float lo, float hi) { unsigned r; asm volatile("v_cvt_pk_bf16_f32 %0, %1, %2" : "=v"(r) : "v"(lo), "v"(hi)); return r; }
;     __device__ __forceinline__ void operator()(const f32x4 (&acc)[2][2][4][2], const Unit& u, int wr, int wc, int fr, int fq) const {
;     ...
;                 const int r = row0 + ai * HALF + m * 16;
;                 const float rs = __builtin_amdgcn_rsqf((float)ss[r] * (1.0f / 1048576.0f) * (1.0f / 1024.0f) + EPS);
;                 bf16_t* rowp = O + (size_t)r * ldc + colt + wc * 32 + 8 * fq;
; #pragma unroll
;                 for (int bj = 0; bj < 2; ++bj) { f32x4 v0 = acc[ai][bj][m][0] * rs, v1 = acc[ai][bj][m][1] * rs;
;                     if (mode == 2) {
; #pragma unroll
;                         for (int e = 0; e < 4; ++e) { float a = fmaxf(v0[e], 0.f), b = fmaxf(v1[e], 0.f); v0[e] = a * a; v1[e] = b * b; } }
;                     if (mode == 1 && colt >= 2048) {
; #pragma unroll
;                         for (int e = 0; e < 4; ++e) { v0[e] = __builtin_amdgcn_rcpf(1.0f + __builtin_amdgcn_exp2f(-1.4426950408889634f * v0[e])); v1[e] = __builtin_amdgcn_rcpf(1.0f + __builtin_amdgcn_exp2f(-1.4426950408889634f * v1[e])); } }
;                     u32x4 w; w.x = cvt_pk_bf16(v0[0], v0[1]); w.y = cvt_pk_bf16(v0[2], v0[3]); w.z = cvt_pk_bf16(v1[0], v1[1]); w.w = cvt_pk_bf16(v1[2], v1[3]);
;                     *(u32x4*)(rowp + bj * HALF) = w; }
.LBB0_364:
	v_mad_i64_i32 v[84:85], s[42:43], s54, v160, 0
	s_ashr_i32 s77, s76, 31
	v_lshl_add_u64 v[84:85], v[84:85], 1, s[28:29]
	v_lshl_add_u64 v[84:85], s[76:77], 1, v[84:85]
	s_lshl_b32 s34, s83, 1
	v_lshl_add_u64 v[84:85], v[84:85], 0, s[34:35]
	v_lshlrev_b32_e32 v112, 1, v154
	v_lshl_add_u64 v[84:85], v[84:85], 0, v[112:113]
	v_mov_b32_e32 v210, s54
	v_mov_b32_e32 v211, 0
	v_lshlrev_b32_e32 v210, 5, v210
	v_mov_b32_e32 v213, 0
	v_mul_u32_u24_e32 v212, 5, v210
	v_lshl_add_u64 v[208:209], v[84:85], 0, v[210:211]
	v_cvt_pk_bf16_f32 v90, v90, v91
	v_cvt_pk_bf16_f32 v91, v86, v87
	v_cvt_pk_bf16_f32 v92, v92, v93
	v_mov_b32_e32 v83, v82
	v_cvt_pk_bf16_f32 v93, v88, v89
	global_store_dwordx4 v[84:85], v[90:93], off
	v_mov_b32_e32 v88, v82
	v_mov_b32_e32 v89, v82
	v_cndmask_b32_e64 v92, 0, 1, s[50:51]
	v_pk_mul_f32 v[86:87], v[136:137], v[88:89]
	v_pk_mul_f32 v[90:91], v[134:135], v[82:83]
	v_pk_mul_f32 v[88:89], v[132:133], v[88:89]
	v_cmp_ne_u32_e64 s[42:43], 1, v92
	s_andn2_b64 vcc, exec, s[50:51]
	v_pk_mul_f32 v[82:83], v[130:131], v[82:83]
	s_cbranch_vccnz .LBB0_366
	v_max_f32_e32 v90, 0, v90
	v_max_f32_e32 v82, 0, v82
	v_max_f32_e32 v91, 0, v91
	v_max_f32_e32 v83, 0, v83
	v_max_f32_e32 v86, 0, v86
	v_max_f32_e32 v88, 0, v88
	v_max_f32_e32 v87, 0, v87
	v_max_f32_e32 v89, 0, v89
	v_pk_mul_f32 v[90:91], v[90:91], v[90:91]
	v_pk_mul_f32 v[86:87], v[86:87], v[86:87]
	v_pk_mul_f32 v[82:83], v[82:83], v[82:83]
	v_pk_mul_f32 v[88:89], v[88:89], v[88:89]

; __device__ __forceinline__ unsigned cvt_pk_bf16(float lo, float hi) { unsigned r; asm volatile("v_cvt_pk_bf16_f32 %0, %1, %2" : "=v"(r) : "v"(lo), "v"(hi)); return r; }
;     __device__ __forceinline__ void operator()(const f32x4 (&acc)[2][2][4][2], const Unit& u, int wr, int wc, int fr, int fq) const {
;     ...
;                 bf16_t* rowp = O + (size_t)r * ldc + colt + wc * 32 + 8 * fq;
; #pragma unroll
;                 for (int bj = 0; bj < 2; ++bj) { f32x4 v0 = acc[ai][bj][m][0] * rs, v1 = acc[ai][bj][m][1] * rs;
;                     if (mode == 2) {
; #pragma unroll
;                         for (int e = 0; e < 4; ++e) { float a = fmaxf(v0[e], 0.f), b = fmaxf(v1[e], 0.f); v0[e] = a * a; v1[e] = b * b; } }
;                     if (mode == 1 && colt >= 2048) {
; #pragma unroll
;                         for (int e = 0; e < 4; ++e) { v0[e] = __builtin_amdgcn_rcpf(1.0f + __builtin_amdgcn_exp2f(-1.4426950408889634f * v0[e])); v1[e] = __builtin_amdgcn_rcpf(1.0f + __builtin_amdgcn_exp2f(-1.4426950408889634f * v1[e])); } }
;                     u32x4 w; w.x = cvt_pk_bf16(v0[0], v0[1]); w.y = cvt_pk_bf16(v0[2], v0[3]); w.z = cvt_pk_bf16(v1[0], v1[1]); w.w = cvt_pk_bf16(v1[2], v1[3]);
;                     *(u32x4*)(rowp + bj * HALF) = w; }
.LBB0_372:
	v_mov_b32_e32 v83, v82
	v_cvt_pk_bf16_f32 v90, v90, v91
	v_cvt_pk_bf16_f32 v91, v86, v87
	v_cvt_pk_bf16_f32 v92, v92, v93
	v_cvt_pk_bf16_f32 v93, v88, v89
	v_mov_b32_e32 v88, v82
	v_mov_b32_e32 v89, v82
	global_store_dwordx4 v[208:209], v[90:93], off
	v_pk_mul_f32 v[86:87], v[120:121], v[88:89]
	v_pk_mul_f32 v[88:89], v[116:117], v[88:89]
	v_pk_mul_f32 v[90:91], v[118:119], v[82:83]
	s_and_b64 vcc, exec, s[42:43]
	v_pk_mul_f32 v[82:83], v[114:115], v[82:83]
	s_cbranch_vccnz .LBB0_374
	v_max_f32_e32 v90, 0, v90
	v_max_f32_e32 v82, 0, v82
	v_max_f32_e32 v91, 0, v91
	v_max_f32_e32 v83, 0, v83
	v_max_f32_e32 v86, 0, v86
	v_max_f32_e32 v88, 0, v88
	v_max_f32_e32 v87, 0, v87
	v_max_f32_e32 v89, 0, v89
	v_pk_mul_f32 v[90:91], v[90:91], v[90:91]
	v_pk_mul_f32 v[86:87], v[86:87], v[86:87]
	v_pk_mul_f32 v[82:83], v[82:83], v[82:83]
	v_pk_mul_f32 v[88:89], v[88:89], v[88:89]

; __device__ __forceinline__ unsigned cvt_pk_bf16(float lo, float hi) { unsigned r; asm volatile("v_cvt_pk_bf16_f32 %0, %1, %2" : "=v"(r) : "v"(lo), "v"(hi)); return r; }
;     __device__ __forceinline__ void operator()(const f32x4 (&acc)[2][2][4][2], const Unit& u, int wr, int wc, int fr, int fq) const {
;     ...
;                 const int r = row0 + ai * HALF + m * 16;
;                 const float rs = __builtin_amdgcn_rsqf((float)ss[r] * (1.0f / 1048576.0f) * (1.0f / 1024.0f) + EPS);
;                 bf16_t* rowp = O + (size_t)r * ldc + colt + wc * 32 + 8 * fq;
; #pragma unroll
;                 for (int bj = 0; bj < 2; ++bj) { f32x4 v0 = acc[ai][bj][m][0] * rs, v1 = acc[ai][bj][m][1] * rs;
;                     if (mode == 2) {
; #pragma unroll
;                         for (int e = 0; e < 4; ++e) { float a = fmaxf(v0[e], 0.f), b = fmaxf(v1[e], 0.f); v0[e] = a * a; v1[e] = b * b; } }
;                     if (mode == 1 && colt >= 2048) {
; #pragma unroll
;                         for (int e = 0; e < 4; ++e) { v0[e] = __builtin_amdgcn_rcpf(1.0f + __builtin_amdgcn_exp2f(-1.4426950408889634f * v0[e])); v1[e] = __builtin_amdgcn_rcpf(1.0f + __builtin_amdgcn_exp2f(-1.4426950408889634f * v1[e])); } }
;                     u32x4 w; w.x = cvt_pk_bf16(v0[0], v0[1]); w.y = cvt_pk_bf16(v0[2], v0[3]); w.z = cvt_pk_bf16(v1[0], v1[1]); w.w = cvt_pk_bf16(v1[2], v1[3]);
;                     *(u32x4*)(rowp + bj * HALF) = w; }
.LBB0_376:
	v_cvt_pk_bf16_f32 v90, v90, v91
	v_cvt_pk_bf16_f32 v91, v86, v87
	v_cvt_pk_bf16_f32 v92, v82, v83
	v_cvt_pk_bf16_f32 v93, v88, v89
	global_store_dwordx4 v[208:209], v[90:93], off offset:256
	v_lshl_add_u64 v[208:209], v[208:209], 0, v[210:211]
	s_and_b64 vcc, exec, s[42:43]
	s_nop 1
	v_cvt_f32_u32_e32 v83, v197
	v_cvt_f32_u32_e32 v82, v196
	v_fmamk_f32 v82, v83, 0x4f800000, v82
	v_fmamk_f32 v82, v82, 0x30800000, v229
	v_rsq_f32_e32 v82, v82
	s_nop 0
	v_pk_mul_f32 v[86:87], v[110:111], v[82:83] op_sel_hi:[1,0]
	v_pk_mul_f32 v[90:91], v[108:109], v[82:83] op_sel_hi:[1,0]
	v_pk_mul_f32 v[88:89], v[106:107], v[82:83] op_sel_hi:[1,0]
	v_pk_mul_f32 v[92:93], v[104:105], v[82:83] op_sel_hi:[1,0]
	s_cbranch_vccnz .LBB0_378
	v_max_f32_e32 v84, 0, v90
	v_max_f32_e32 v92, 0, v92
	v_max_f32_e32 v85, 0, v91
	v_max_f32_e32 v93, 0, v93
	v_max_f32_e32 v86, 0, v86
	v_max_f32_e32 v88, 0, v88
	v_max_f32_e32 v87, 0, v87
	v_max_f32_e32 v89, 0, v89
	v_pk_mul_f32 v[90:91], v[84:85], v[84:85]
	v_pk_mul_f32 v[86:87], v[86:87], v[86:87]
	v_pk_mul_f32 v[92:93], v[92:93], v[92:93]
	v_pk_mul_f32 v[88:89], v[88:89], v[88:89]

; __device__ __forceinline__ unsigned cvt_pk_bf16(float lo, float hi) { unsigned r; asm volatile("v_cvt_pk_bf16_f32 %0, %1, %2" : "=v"(r) : "v"(lo), "v"(hi)); return r; }
;     __device__ __forceinline__ void operator()(const f32x4 (&acc)[2][2][4][2], const Unit& u, int wr, int wc, int fr, int fq) const {
;     ...
;                 bf16_t* rowp = O + (size_t)r * ldc + colt + wc * 32 + 8 * fq;
; #pragma unroll
;                 for (int bj = 0; bj < 2; ++bj) { f32x4 v0 = acc[ai][bj][m][0] * rs, v1 = acc[ai][bj][m][1] * rs;
;                     if (mode == 2) {
; #pragma unroll
;                         for (int e = 0; e < 4; ++e) { float a = fmaxf(v0[e], 0.f), b = fmaxf(v1[e], 0.f); v0[e] = a * a; v1[e] = b * b; } }
;                     if (mode == 1 && colt >= 2048) {
; #pragma unroll
;                         for (int e = 0; e < 4; ++e) { v0[e] = __builtin_amdgcn_rcpf(1.0f + __builtin_amdgcn_exp2f(-1.4426950408889634f * v0[e])); v1[e] = __builtin_amdgcn_rcpf(1.0f + __builtin_amdgcn_exp2f(-1.4426950408889634f * v1[e])); } }
;                     u32x4 w; w.x = cvt_pk_bf16(v0[0], v0[1]); w.y = cvt_pk_bf16(v0[2], v0[3]); w.z = cvt_pk_bf16(v1[0], v1[1]); w.w = cvt_pk_bf16(v1[2], v1[3]);
;                     *(u32x4*)(rowp + bj * HALF) = w; }
.LBB0_380:
	v_mov_b32_e32 v83, v82
	v_cvt_pk_bf16_f32 v90, v90, v91
	v_cvt_pk_bf16_f32 v91, v86, v87
	v_cvt_pk_bf16_f32 v92, v92, v93
	v_cvt_pk_bf16_f32 v93, v88, v89
	v_mov_b32_e32 v88, v82
	v_mov_b32_e32 v89, v82
	global_store_dwordx4 v[208:209], v[90:93], off
	v_pk_mul_f32 v[86:87], v[102:103], v[88:89]
	v_pk_mul_f32 v[88:89], v[98:99], v[88:89]
	v_pk_mul_f32 v[90:91], v[100:101], v[82:83]
	s_and_b64 vcc, exec, s[42:43]
	v_pk_mul_f32 v[82:83], v[96:97], v[82:83]
	s_cbranch_vccnz .LBB0_382
	v_max_f32_e32 v90, 0, v90
	v_max_f32_e32 v82, 0, v82
	v_max_f32_e32 v91, 0, v91
	v_max_f32_e32 v83, 0, v83
	v_max_f32_e32 v86, 0, v86
	v_max_f32_e32 v88, 0, v88
	v_max_f32_e32 v87, 0, v87
	v_max_f32_e32 v89, 0, v89
	v_pk_mul_f32 v[90:91], v[90:91], v[90:91]
	v_pk_mul_f32 v[86:87], v[86:87], v[86:87]
	v_pk_mul_f32 v[82:83], v[82:83], v[82:83]
	v_pk_mul_f32 v[88:89], v[88:89], v[88:89]

; __device__ __forceinline__ unsigned cvt_pk_bf16(float lo, float hi) { unsigned r; asm volatile("v_cvt_pk_bf16_f32 %0, %1, %2" : "=v"(r) : "v"(lo), "v"(hi)); return r; }
;     __device__ __forceinline__ void operator()(const f32x4 (&acc)[2][2][4][2], const Unit& u, int wr, int wc, int fr, int fq) const {
;     ...
;                 const int r = row0 + ai * HALF + m * 16;
;                 const float rs = __builtin_amdgcn_rsqf((float)ss[r] * (1.0f / 1048576.0f) * (1.0f / 1024.0f) + EPS);
;                 bf16_t* rowp = O + (size_t)r * ldc + colt + wc * 32 + 8 * fq;
; #pragma unroll
;                 for (int bj = 0; bj < 2; ++bj) { f32x4 v0 = acc[ai][bj][m][0] * rs, v1 = acc[ai][bj][m][1] * rs;
;                     if (mode == 2) {
; #pragma unroll
;                         for (int e = 0; e < 4; ++e) { float a = fmaxf(v0[e], 0.f), b = fmaxf(v1[e], 0.f); v0[e] = a * a; v1[e] = b * b; } }
;                     if (mode == 1 && colt >= 2048) {
; #pragma unroll
;                         for (int e = 0; e < 4; ++e) { v0[e] = __builtin_amdgcn_rcpf(1.0f + __builtin_amdgcn_exp2f(-1.4426950408889634f * v0[e])); v1[e] = __builtin_amdgcn_rcpf(1.0f + __builtin_amdgcn_exp2f(-1.4426950408889634f * v1[e])); } }
;                     u32x4 w; w.x = cvt_pk_bf16(v0[0], v0[1]); w.y = cvt_pk_bf16(v0[2], v0[3]); w.z = cvt_pk_bf16(v1[0], v1[1]); w.w = cvt_pk_bf16(v1[2], v1[3]);
;                     *(u32x4*)(rowp + bj * HALF) = w; }
.LBB0_384:
	v_cvt_pk_bf16_f32 v90, v90, v91
	v_cvt_pk_bf16_f32 v91, v86, v87
	v_cvt_pk_bf16_f32 v92, v82, v83
	v_cvt_pk_bf16_f32 v93, v88, v89
	global_store_dwordx4 v[208:209], v[90:93], off offset:256
	v_lshl_add_u64 v[208:209], v[208:209], 0, v[210:211]
	s_and_b64 vcc, exec, s[42:43]
	s_nop 1
	v_cvt_f32_u32_e32 v83, v199
	v_cvt_f32_u32_e32 v82, v198
	v_fmamk_f32 v82, v83, 0x4f800000, v82
	v_fmamk_f32 v82, v82, 0x30800000, v229
	v_rsq_f32_e32 v82, v82
	s_nop 0
	v_pk_mul_f32 v[86:87], v[78:79], v[82:83] op_sel_hi:[1,0]
	v_pk_mul_f32 v[90:91], v[76:77], v[82:83] op_sel_hi:[1,0]
	v_pk_mul_f32 v[88:89], v[74:75], v[82:83] op_sel_hi:[1,0]
	v_pk_mul_f32 v[92:93], v[72:73], v[82:83] op_sel_hi:[1,0]
	s_cbranch_vccnz .LBB0_386
	v_max_f32_e32 v84, 0, v90
	v_max_f32_e32 v92, 0, v92
	v_max_f32_e32 v85, 0, v91
	v_max_f32_e32 v93, 0, v93
	v_max_f32_e32 v86, 0, v86
	v_max_f32_e32 v88, 0, v88
	v_max_f32_e32 v87, 0, v87
	v_max_f32_e32 v89, 0, v89
	v_pk_mul_f32 v[90:91], v[84:85], v[84:85]
	v_pk_mul_f32 v[86:87], v[86:87], v[86:87]
	v_pk_mul_f32 v[92:93], v[92:93], v[92:93]
	v_pk_mul_f32 v[88:89], v[88:89], v[88:89]

; __device__ __forceinline__ unsigned cvt_pk_bf16(float lo, float hi) { unsigned r; asm volatile("v_cvt_pk_bf16_f32 %0, %1, %2" : "=v"(r) : "v"(lo), "v"(hi)); return r; }
;     __device__ __forceinline__ void operator()(const f32x4 (&acc)[2][2][4][2], const Unit& u, int wr, int wc, int fr, int fq) const {
;     ...
;                 bf16_t* rowp = O + (size_t)r * ldc + colt + wc * 32 + 8 * fq;
; #pragma unroll
;                 for (int bj = 0; bj < 2; ++bj) { f32x4 v0 = acc[ai][bj][m][0] * rs, v1 = acc[ai][bj][m][1] * rs;
;                     if (mode == 2) {
; #pragma unroll
;                         for (int e = 0; e < 4; ++e) { float a = fmaxf(v0[e], 0.f), b = fmaxf(v1[e], 0.f); v0[e] = a * a; v1[e] = b * b; } }
;                     if (mode == 1 && colt >= 2048) {
; #pragma unroll
;                         for (int e = 0; e < 4; ++e) { v0[e] = __builtin_amdgcn_rcpf(1.0f + __builtin_amdgcn_exp2f(-1.4426950408889634f * v0[e])); v1[e] = __builtin_amdgcn_rcpf(1.0f + __builtin_amdgcn_exp2f(-1.4426950408889634f * v1[e])); } }
;                     u32x4 w; w.x = cvt_pk_bf16(v0[0], v0[1]); w.y = cvt_pk_bf16(v0[2], v0[3]); w.z = cvt_pk_bf16(v1[0], v1[1]); w.w = cvt_pk_bf16(v1[2], v1[3]);
;                     *(u32x4*)(rowp + bj * HALF) = w; }
.LBB0_388:
	v_mov_b32_e32 v83, v82
	v_cvt_pk_bf16_f32 v90, v90, v91
	v_cvt_pk_bf16_f32 v91, v86, v87
	v_cvt_pk_bf16_f32 v92, v92, v93
	v_cvt_pk_bf16_f32 v93, v88, v89
	v_mov_b32_e32 v88, v82
	v_mov_b32_e32 v89, v82
	global_store_dwordx4 v[208:209], v[90:93], off
	v_pk_mul_f32 v[86:87], v[70:71], v[88:89]
	v_pk_mul_f32 v[88:89], v[66:67], v[88:89]
	v_pk_mul_f32 v[90:91], v[68:69], v[82:83]
	s_and_b64 vcc, exec, s[42:43]
	v_pk_mul_f32 v[82:83], v[64:65], v[82:83]
	s_cbranch_vccnz .LBB0_390
	v_max_f32_e32 v90, 0, v90
	v_max_f32_e32 v82, 0, v82
	v_max_f32_e32 v91, 0, v91
	v_max_f32_e32 v83, 0, v83
	v_max_f32_e32 v86, 0, v86
	v_max_f32_e32 v88, 0, v88
	v_max_f32_e32 v87, 0, v87
	v_max_f32_e32 v89, 0, v89
	v_pk_mul_f32 v[90:91], v[90:91], v[90:91]
	v_pk_mul_f32 v[86:87], v[86:87], v[86:87]
	v_pk_mul_f32 v[82:83], v[82:83], v[82:83]
	v_pk_mul_f32 v[88:89], v[88:89], v[88:89]

; __device__ __forceinline__ unsigned cvt_pk_bf16(float lo, float hi) { unsigned r; asm volatile("v_cvt_pk_bf16_f32 %0, %1, %2" : "=v"(r) : "v"(lo), "v"(hi)); return r; }
;     __device__ __forceinline__ void operator()(const f32x4 (&acc)[2][2][4][2], const Unit& u, int wr, int wc, int fr, int fq) const {
;     ...
;                 const int r = row0 + ai * HALF + m * 16;
;                 const float rs = __builtin_amdgcn_rsqf((float)ss[r] * (1.0f / 1048576.0f) * (1.0f / 1024.0f) + EPS);
;                 bf16_t* rowp = O + (size_t)r * ldc + colt + wc * 32 + 8 * fq;
; #pragma unroll
;                 for (int bj = 0; bj < 2; ++bj) { f32x4 v0 = acc[ai][bj][m][0] * rs, v1 = acc[ai][bj][m][1] * rs;
;                     if (mode == 2) {
; #pragma unroll
;                         for (int e = 0; e < 4; ++e) { float a = fmaxf(v0[e], 0.f), b = fmaxf(v1[e], 0.f); v0[e] = a * a; v1[e] = b * b; } }
;                     if (mode == 1 && colt >= 2048) {
; #pragma unroll
;                         for (int e = 0; e < 4; ++e) { v0[e] = __builtin_amdgcn_rcpf(1.0f + __builtin_amdgcn_exp2f(-1.4426950408889634f * v0[e])); v1[e] = __builtin_amdgcn_rcpf(1.0f + __builtin_amdgcn_exp2f(-1.4426950408889634f * v1[e])); } }
;                     u32x4 w; w.x = cvt_pk_bf16(v0[0], v0[1]); w.y = cvt_pk_bf16(v0[2], v0[3]); w.z = cvt_pk_bf16(v1[0], v1[1]); w.w = cvt_pk_bf16(v1[2], v1[3]);
;                     *(u32x4*)(rowp + bj * HALF) = w; }
.LBB0_392:
	v_cvt_pk_bf16_f32 v90, v90, v91
	v_cvt_pk_bf16_f32 v91, v86, v87
	v_cvt_pk_bf16_f32 v92, v82, v83
	v_cvt_pk_bf16_f32 v93, v88, v89
	global_store_dwordx4 v[208:209], v[90:93], off offset:256
	v_lshl_add_u64 v[208:209], v[208:209], 0, v[212:213]
	s_and_b64 vcc, exec, s[42:43]
	s_nop 1
	v_cvt_f32_u32_e32 v83, v201
	v_cvt_f32_u32_e32 v82, v200
	v_fmamk_f32 v82, v83, 0x4f800000, v82
	v_fmamk_f32 v82, v82, 0x30800000, v229
	v_rsq_f32_e32 v82, v82
	s_nop 0
	v_pk_mul_f32 v[86:87], v[62:63], v[82:83] op_sel_hi:[1,0]
	v_pk_mul_f32 v[90:91], v[60:61], v[82:83] op_sel_hi:[1,0]
	v_pk_mul_f32 v[88:89], v[58:59], v[82:83] op_sel_hi:[1,0]
	v_pk_mul_f32 v[92:93], v[56:57], v[82:83] op_sel_hi:[1,0]
	s_cbranch_vccnz .LBB0_394
	v_max_f32_e32 v84, 0, v90
	v_max_f32_e32 v92, 0, v92
	v_max_f32_e32 v85, 0, v91
	v_max_f32_e32 v93, 0, v93
	v_max_f32_e32 v86, 0, v86
	v_max_f32_e32 v88, 0, v88
	v_max_f32_e32 v87, 0, v87
	v_max_f32_e32 v89, 0, v89
	v_pk_mul_f32 v[90:91], v[84:85], v[84:85]
	v_pk_mul_f32 v[86:87], v[86:87], v[86:87]
	v_pk_mul_f32 v[92:93], v[92:93], v[92:93]
	v_pk_mul_f32 v[88:89], v[88:89], v[88:89]

; __device__ __forceinline__ unsigned cvt_pk_bf16(float lo, float hi) { unsigned r; asm volatile("v_cvt_pk_bf16_f32 %0, %1, %2" : "=v"(r) : "v"(lo), "v"(hi)); return r; }
;     __device__ __forceinline__ void operator()(const f32x4 (&acc)[2][2][4][2], const Unit& u, int wr, int wc, int fr, int fq) const {
;     ...
;                 bf16_t* rowp = O + (size_t)r * ldc + colt + wc * 32 + 8 * fq;
; #pragma unroll
;                 for (int bj = 0; bj < 2; ++bj) { f32x4 v0 = acc[ai][bj][m][0] * rs, v1 = acc[ai][bj][m][1] * rs;
;                     if (mode == 2) {
; #pragma unroll
;                         for (int e = 0; e < 4; ++e) { float a = fmaxf(v0[e], 0.f), b = fmaxf(v1[e], 0.f); v0[e] = a * a; v1[e] = b * b; } }
;                     if (mode == 1 && colt >= 2048) {
; #pragma unroll
;                         for (int e = 0; e < 4; ++e) { v0[e] = __builtin_amdgcn_rcpf(1.0f + __builtin_amdgcn_exp2f(-1.4426950408889634f * v0[e])); v1[e] = __builtin_amdgcn_rcpf(1.0f + __builtin_amdgcn_exp2f(-1.4426950408889634f * v1[e])); } }
;                     u32x4 w; w.x = cvt_pk_bf16(v0[0], v0[1]); w.y = cvt_pk_bf16(v0[2], v0[3]); w.z = cvt_pk_bf16(v1[0], v1[1]); w.w = cvt_pk_bf16(v1[2], v1[3]);
;                     *(u32x4*)(rowp + bj * HALF) = w; }
.LBB0_396:
	v_mov_b32_e32 v83, v82
	v_cvt_pk_bf16_f32 v90, v90, v91
	v_cvt_pk_bf16_f32 v91, v86, v87
	v_cvt_pk_bf16_f32 v92, v92, v93
	v_cvt_pk_bf16_f32 v93, v88, v89
	v_mov_b32_e32 v88, v82
	v_mov_b32_e32 v89, v82
	global_store_dwordx4 v[208:209], v[90:93], off
	v_pk_mul_f32 v[86:87], v[54:55], v[88:89]
	v_pk_mul_f32 v[88:89], v[50:51], v[88:89]
	v_pk_mul_f32 v[90:91], v[52:53], v[82:83]
	s_and_b64 vcc, exec, s[42:43]
	v_pk_mul_f32 v[82:83], v[48:49], v[82:83]
	s_cbranch_vccnz .LBB0_398
	v_max_f32_e32 v90, 0, v90
	v_max_f32_e32 v82, 0, v82
	v_max_f32_e32 v91, 0, v91
	v_max_f32_e32 v83, 0, v83
	v_max_f32_e32 v86, 0, v86
	v_max_f32_e32 v88, 0, v88
	v_max_f32_e32 v87, 0, v87
	v_max_f32_e32 v89, 0, v89
	v_pk_mul_f32 v[90:91], v[90:91], v[90:91]
	v_pk_mul_f32 v[86:87], v[86:87], v[86:87]
	v_pk_mul_f32 v[82:83], v[82:83], v[82:83]
	v_pk_mul_f32 v[88:89], v[88:89], v[88:89]

; __device__ __forceinline__ unsigned cvt_pk_bf16(float lo, float hi) { unsigned r; asm volatile("v_cvt_pk_bf16_f32 %0, %1, %2" : "=v"(r) : "v"(lo), "v"(hi)); return r; }
;     __device__ __forceinline__ void operator()(const f32x4 (&acc)[2][2][4][2], const Unit& u, int wr, int wc, int fr, int fq) const {
;     ...
;                 const int r = row0 + ai * HALF + m * 16;
;                 const float rs = __builtin_amdgcn_rsqf((float)ss[r] * (1.0f / 1048576.0f) * (1.0f / 1024.0f) + EPS);
;                 bf16_t* rowp = O + (size_t)r * ldc + colt + wc * 32 + 8 * fq;
; #pragma unroll
;                 for (int bj = 0; bj < 2; ++bj) { f32x4 v0 = acc[ai][bj][m][0] * rs, v1 = acc[ai][bj][m][1] * rs;
;                     if (mode == 2) {
; #pragma unroll
;                         for (int e = 0; e < 4; ++e) { float a = fmaxf(v0[e], 0.f), b = fmaxf(v1[e], 0.f); v0[e] = a * a; v1[e] = b * b; } }
;                     if (mode == 1 && colt >= 2048) {
; #pragma unroll
;                         for (int e = 0; e < 4; ++e) { v0[e] = __builtin_amdgcn_rcpf(1.0f + __builtin_amdgcn_exp2f(-1.4426950408889634f * v0[e])); v1[e] = __builtin_amdgcn_rcpf(1.0f + __builtin_amdgcn_exp2f(-1.4426950408889634f * v1[e])); } }
;                     u32x4 w; w.x = cvt_pk_bf16(v0[0], v0[1]); w.y = cvt_pk_bf16(v0[2], v0[3]); w.z = cvt_pk_bf16(v1[0], v1[1]); w.w = cvt_pk_bf16(v1[2], v1[3]);
;                     *(u32x4*)(rowp + bj * HALF) = w; }
.LBB0_400:
	v_cvt_pk_bf16_f32 v90, v90, v91
	v_cvt_pk_bf16_f32 v91, v86, v87
	v_cvt_pk_bf16_f32 v92, v82, v83
	v_cvt_pk_bf16_f32 v93, v88, v89
	global_store_dwordx4 v[208:209], v[90:93], off offset:256
	v_lshl_add_u64 v[208:209], v[208:209], 0, v[210:211]
	s_and_b64 vcc, exec, s[42:43]
	s_nop 1
	v_cvt_f32_u32_e32 v83, v203
	v_cvt_f32_u32_e32 v82, v202
	v_fmamk_f32 v82, v83, 0x4f800000, v82
	v_fmamk_f32 v82, v82, 0x30800000, v229
	v_rsq_f32_e32 v82, v82
	s_nop 0
	v_pk_mul_f32 v[86:87], v[46:47], v[82:83] op_sel_hi:[1,0]
	v_pk_mul_f32 v[90:91], v[44:45], v[82:83] op_sel_hi:[1,0]
	v_pk_mul_f32 v[88:89], v[42:43], v[82:83] op_sel_hi:[1,0]
	v_pk_mul_f32 v[92:93], v[40:41], v[82:83] op_sel_hi:[1,0]
	s_cbranch_vccnz .LBB0_402
	v_max_f32_e32 v84, 0, v90
	v_max_f32_e32 v92, 0, v92
	v_max_f32_e32 v85, 0, v91
	v_max_f32_e32 v93, 0, v93
	v_max_f32_e32 v86, 0, v86
	v_max_f32_e32 v88, 0, v88
	v_max_f32_e32 v87, 0, v87
	v_max_f32_e32 v89, 0, v89
	v_pk_mul_f32 v[90:91], v[84:85], v[84:85]
	v_pk_mul_f32 v[86:87], v[86:87], v[86:87]
	v_pk_mul_f32 v[92:93], v[92:93], v[92:93]
	v_pk_mul_f32 v[88:89], v[88:89], v[88:89]

; __device__ __forceinline__ unsigned cvt_pk_bf16(float lo, float hi) { unsigned r; asm volatile("v_cvt_pk_bf16_f32 %0, %1, %2" : "=v"(r) : "v"(lo), "v"(hi)); return r; }
;     __device__ __forceinline__ void operator()(const f32x4 (&acc)[2][2][4][2], const Unit& u, int wr, int wc, int fr, int fq) const {
;     ...
;                 bf16_t* rowp = O + (size_t)r * ldc + colt + wc * 32 + 8 * fq;
; #pragma unroll
;                 for (int bj = 0; bj < 2; ++bj) { f32x4 v0 = acc[ai][bj][m][0] * rs, v1 = acc[ai][bj][m][1] * rs;
;                     if (mode == 2) {
; #pragma unroll
;                         for (int e = 0; e < 4; ++e) { float a = fmaxf(v0[e], 0.f), b = fmaxf(v1[e], 0.f); v0[e] = a * a; v1[e] = b * b; } }
;                     if (mode == 1 && colt >= 2048) {
; #pragma unroll
;                         for (int e = 0; e < 4; ++e) { v0[e] = __builtin_amdgcn_rcpf(1.0f + __builtin_amdgcn_exp2f(-1.4426950408889634f * v0[e])); v1[e] = __builtin_amdgcn_rcpf(1.0f + __builtin_amdgcn_exp2f(-1.4426950408889634f * v1[e])); } }
;                     u32x4 w; w.x = cvt_pk_bf16(v0[0], v0[1]); w.y = cvt_pk_bf16(v0[2], v0[3]); w.z = cvt_pk_bf16(v1[0], v1[1]); w.w = cvt_pk_bf16(v1[2], v1[3]);
;                     *(u32x4*)(rowp + bj * HALF) = w; }
.LBB0_404:
	v_mov_b32_e32 v83, v82
	v_cvt_pk_bf16_f32 v90, v90, v91
	v_cvt_pk_bf16_f32 v91, v86, v87
	v_cvt_pk_bf16_f32 v92, v92, v93
	v_cvt_pk_bf16_f32 v93, v88, v89
	v_mov_b32_e32 v88, v82
	v_mov_b32_e32 v89, v82
	global_store_dwordx4 v[208:209], v[90:93], off
	v_pk_mul_f32 v[86:87], v[38:39], v[88:89]
	v_pk_mul_f32 v[88:89], v[34:35], v[88:89]
	v_pk_mul_f32 v[90:91], v[36:37], v[82:83]
	s_and_b64 vcc, exec, s[42:43]
	v_pk_mul_f32 v[82:83], v[32:33], v[82:83]
	s_cbranch_vccnz .LBB0_406
	v_max_f32_e32 v90, 0, v90
	v_max_f32_e32 v82, 0, v82
	v_max_f32_e32 v91, 0, v91
	v_max_f32_e32 v83, 0, v83
	v_max_f32_e32 v86, 0, v86
	v_max_f32_e32 v88, 0, v88
	v_max_f32_e32 v87, 0, v87
	v_max_f32_e32 v89, 0, v89
	v_pk_mul_f32 v[90:91], v[90:91], v[90:91]
	v_pk_mul_f32 v[86:87], v[86:87], v[86:87]
	v_pk_mul_f32 v[82:83], v[82:83], v[82:83]
	v_pk_mul_f32 v[88:89], v[88:89], v[88:89]

; __device__ __forceinline__ unsigned cvt_pk_bf16(float lo, float hi) { unsigned r; asm volatile("v_cvt_pk_bf16_f32 %0, %1, %2" : "=v"(r) : "v"(lo), "v"(hi)); return r; }
;     __device__ __forceinline__ void operator()(const f32x4 (&acc)[2][2][4][2], const Unit& u, int wr, int wc, int fr, int fq) const {
;     ...
;                 const int r = row0 + ai * HALF + m * 16;
;                 const float rs = __builtin_amdgcn_rsqf((float)ss[r] * (1.0f / 1048576.0f) * (1.0f / 1024.0f) + EPS);
;                 bf16_t* rowp = O + (size_t)r * ldc + colt + wc * 32 + 8 * fq;
; #pragma unroll
;                 for (int bj = 0; bj < 2; ++bj) { f32x4 v0 = acc[ai][bj][m][0] * rs, v1 = acc[ai][bj][m][1] * rs;
;                     if (mode == 2) {
; #pragma unroll
;                         for (int e = 0; e < 4; ++e) { float a = fmaxf(v0[e], 0.f), b = fmaxf(v1[e], 0.f); v0[e] = a * a; v1[e] = b * b; } }
;                     if (mode == 1 && colt >= 2048) {
; #pragma unroll
;                         for (int e = 0; e < 4; ++e) { v0[e] = __builtin_amdgcn_rcpf(1.0f + __builtin_amdgcn_exp2f(-1.4426950408889634f * v0[e])); v1[e] = __builtin_amdgcn_rcpf(1.0f + __builtin_amdgcn_exp2f(-1.4426950408889634f * v1[e])); } }
;                     u32x4 w; w.x = cvt_pk_bf16(v0[0], v0[1]); w.y = cvt_pk_bf16(v0[2], v0[3]); w.z = cvt_pk_bf16(v1[0], v1[1]); w.w = cvt_pk_bf16(v1[2], v1[3]);
;                     *(u32x4*)(rowp + bj * HALF) = w; }
.LBB0_408:
	v_cvt_pk_bf16_f32 v90, v90, v91
	v_cvt_pk_bf16_f32 v91, v86, v87
	v_cvt_pk_bf16_f32 v92, v82, v83
	v_cvt_pk_bf16_f32 v93, v88, v89
	global_store_dwordx4 v[208:209], v[90:93], off offset:256
	v_lshl_add_u64 v[208:209], v[208:209], 0, v[210:211]
	s_and_b64 vcc, exec, s[42:43]
	s_nop 1
	v_cvt_f32_u32_e32 v83, v205
	v_cvt_f32_u32_e32 v82, v204
	v_fmamk_f32 v82, v83, 0x4f800000, v82
	v_fmamk_f32 v82, v82, 0x30800000, v229
	v_rsq_f32_e32 v82, v82
	s_nop 0
	v_pk_mul_f32 v[86:87], v[30:31], v[82:83] op_sel_hi:[1,0]
	v_pk_mul_f32 v[90:91], v[28:29], v[82:83] op_sel_hi:[1,0]
	v_pk_mul_f32 v[88:89], v[26:27], v[82:83] op_sel_hi:[1,0]
	v_pk_mul_f32 v[92:93], v[24:25], v[82:83] op_sel_hi:[1,0]
	s_cbranch_vccnz .LBB0_410
	v_max_f32_e32 v84, 0, v90
	v_max_f32_e32 v92, 0, v92
	v_max_f32_e32 v85, 0, v91
	v_max_f32_e32 v93, 0, v93
	v_max_f32_e32 v86, 0, v86
	v_max_f32_e32 v88, 0, v88
	v_max_f32_e32 v87, 0, v87
	v_max_f32_e32 v89, 0, v89
	v_pk_mul_f32 v[90:91], v[84:85], v[84:85]
	v_pk_mul_f32 v[86:87], v[86:87], v[86:87]
	v_pk_mul_f32 v[92:93], v[92:93], v[92:93]
	v_pk_mul_f32 v[88:89], v[88:89], v[88:89]

; __device__ __forceinline__ unsigned cvt_pk_bf16(float lo, float hi) { unsigned r; asm volatile("v_cvt_pk_bf16_f32 %0, %1, %2" : "=v"(r) : "v"(lo), "v"(hi)); return r; }
;     __device__ __forceinline__ void operator()(const f32x4 (&acc)[2][2][4][2], const Unit& u, int wr, int wc, int fr, int fq) const {
;     ...
;                 bf16_t* rowp = O + (size_t)r * ldc + colt + wc * 32 + 8 * fq;
; #pragma unroll
;                 for (int bj = 0; bj < 2; ++bj) { f32x4 v0 = acc[ai][bj][m][0] * rs, v1 = acc[ai][bj][m][1] * rs;
;                     if (mode == 2) {
; #pragma unroll
;                         for (int e = 0; e < 4; ++e) { float a = fmaxf(v0[e], 0.f), b = fmaxf(v1[e], 0.f); v0[e] = a * a; v1[e] = b * b; } }
;                     if (mode == 1 && colt >= 2048) {
; #pragma unroll
;                         for (int e = 0; e < 4; ++e) { v0[e] = __builtin_amdgcn_rcpf(1.0f + __builtin_amdgcn_exp2f(-1.4426950408889634f * v0[e])); v1[e] = __builtin_amdgcn_rcpf(1.0f + __builtin_amdgcn_exp2f(-1.4426950408889634f * v1[e])); } }
;                     u32x4 w; w.x = cvt_pk_bf16(v0[0], v0[1]); w.y = cvt_pk_bf16(v0[2], v0[3]); w.z = cvt_pk_bf16(v1[0], v1[1]); w.w = cvt_pk_bf16(v1[2], v1[3]);
;                     *(u32x4*)(rowp + bj * HALF) = w; }
.LBB0_412:
	v_mov_b32_e32 v83, v82
	v_cvt_pk_bf16_f32 v90, v90, v91
	v_cvt_pk_bf16_f32 v91, v86, v87
	v_cvt_pk_bf16_f32 v92, v92, v93
	v_cvt_pk_bf16_f32 v93, v88, v89
	v_mov_b32_e32 v88, v82
	v_mov_b32_e32 v89, v82
	global_store_dwordx4 v[208:209], v[90:93], off
	v_pk_mul_f32 v[86:87], v[22:23], v[88:89]
	v_pk_mul_f32 v[88:89], v[18:19], v[88:89]
	v_pk_mul_f32 v[90:91], v[20:21], v[82:83]
	s_and_b64 vcc, exec, s[42:43]
	v_pk_mul_f32 v[82:83], v[16:17], v[82:83]
	s_cbranch_vccnz .LBB0_414
	v_max_f32_e32 v90, 0, v90
	v_max_f32_e32 v82, 0, v82
	v_max_f32_e32 v91, 0, v91
	v_max_f32_e32 v83, 0, v83
	v_max_f32_e32 v86, 0, v86
	v_max_f32_e32 v88, 0, v88
	v_max_f32_e32 v87, 0, v87
	v_max_f32_e32 v89, 0, v89
	v_pk_mul_f32 v[90:91], v[90:91], v[90:91]
	v_pk_mul_f32 v[86:87], v[86:87], v[86:87]
	v_pk_mul_f32 v[82:83], v[82:83], v[82:83]
	v_pk_mul_f32 v[88:89], v[88:89], v[88:89]

; __device__ __forceinline__ unsigned cvt_pk_bf16(float lo, float hi) { unsigned r; asm volatile("v_cvt_pk_bf16_f32 %0, %1, %2" : "=v"(r) : "v"(lo), "v"(hi)); return r; }
;     __device__ __forceinline__ void operator()(const f32x4 (&acc)[2][2][4][2], const Unit& u, int wr, int wc, int fr, int fq) const {
;     ...
;                 const int r = row0 + ai * HALF + m * 16;
;                 const float rs = __builtin_amdgcn_rsqf((float)ss[r] * (1.0f / 1048576.0f) * (1.0f / 1024.0f) + EPS);
;                 bf16_t* rowp = O + (size_t)r * ldc + colt + wc * 32 + 8 * fq;
; #pragma unroll
;                 for (int bj = 0; bj < 2; ++bj) { f32x4 v0 = acc[ai][bj][m][0] * rs, v1 = acc[ai][bj][m][1] * rs;
;                     if (mode == 2) {
; #pragma unroll
;                         for (int e = 0; e < 4; ++e) { float a = fmaxf(v0[e], 0.f), b = fmaxf(v1[e], 0.f); v0[e] = a * a; v1[e] = b * b; } }
;                     if (mode == 1 && colt >= 2048) {
; #pragma unroll
;                         for (int e = 0; e < 4; ++e) { v0[e] = __builtin_amdgcn_rcpf(1.0f + __builtin_amdgcn_exp2f(-1.4426950408889634f * v0[e])); v1[e] = __builtin_amdgcn_rcpf(1.0f + __builtin_amdgcn_exp2f(-1.4426950408889634f * v1[e])); } }
;                     u32x4 w; w.x = cvt_pk_bf16(v0[0], v0[1]); w.y = cvt_pk_bf16(v0[2], v0[3]); w.z = cvt_pk_bf16(v1[0], v1[1]); w.w = cvt_pk_bf16(v1[2], v1[3]);
;                     *(u32x4*)(rowp + bj * HALF) = w; }
.LBB0_416:
	v_cvt_pk_bf16_f32 v90, v90, v91
	v_cvt_pk_bf16_f32 v91, v86, v87
	v_cvt_pk_bf16_f32 v92, v82, v83
	v_cvt_pk_bf16_f32 v93, v88, v89
	global_store_dwordx4 v[208:209], v[90:93], off offset:256
	v_lshl_add_u64 v[208:209], v[208:209], 0, v[210:211]
	s_and_b64 vcc, exec, s[42:43]
	s_nop 1
	v_cvt_f32_u32_e32 v81, v207
	v_cvt_f32_u32_e32 v80, v206
	v_fmamk_f32 v80, v81, 0x4f800000, v80
	v_fmamk_f32 v80, v80, 0x30800000, v229
	v_rsq_f32_e32 v80, v80
	s_nop 0
	v_pk_mul_f32 v[84:85], v[14:15], v[80:81] op_sel_hi:[1,0]
	v_pk_mul_f32 v[88:89], v[12:13], v[80:81] op_sel_hi:[1,0]
	v_pk_mul_f32 v[86:87], v[10:11], v[80:81] op_sel_hi:[1,0]
	v_pk_mul_f32 v[90:91], v[8:9], v[80:81] op_sel_hi:[1,0]
	s_cbranch_vccnz .LBB0_418
	v_max_f32_e32 v82, 0, v88
	v_max_f32_e32 v90, 0, v90
	v_max_f32_e32 v83, 0, v89
	v_max_f32_e32 v91, 0, v91
	v_max_f32_e32 v84, 0, v84
	v_max_f32_e32 v86, 0, v86
	v_max_f32_e32 v85, 0, v85
	v_max_f32_e32 v87, 0, v87
	v_pk_mul_f32 v[88:89], v[82:83], v[82:83]
	v_pk_mul_f32 v[84:85], v[84:85], v[84:85]
	v_pk_mul_f32 v[90:91], v[90:91], v[90:91]
	v_pk_mul_f32 v[86:87], v[86:87], v[86:87]

; __device__ __forceinline__ unsigned cvt_pk_bf16(float lo, float hi) { unsigned r; asm volatile("v_cvt_pk_bf16_f32 %0, %1, %2" : "=v"(r) : "v"(lo), "v"(hi)); return r; }
;     __device__ __forceinline__ void operator()(const f32x4 (&acc)[2][2][4][2], const Unit& u, int wr, int wc, int fr, int fq) const {
;     ...
;                 bf16_t* rowp = O + (size_t)r * ldc + colt + wc * 32 + 8 * fq;
; #pragma unroll
;                 for (int bj = 0; bj < 2; ++bj) { f32x4 v0 = acc[ai][bj][m][0] * rs, v1 = acc[ai][bj][m][1] * rs;
;                     if (mode == 2) {
; #pragma unroll
;                         for (int e = 0; e < 4; ++e) { float a = fmaxf(v0[e], 0.f), b = fmaxf(v1[e], 0.f); v0[e] = a * a; v1[e] = b * b; } }
;                     if (mode == 1 && colt >= 2048) {
; #pragma unroll
;                         for (int e = 0; e < 4; ++e) { v0[e] = __builtin_amdgcn_rcpf(1.0f + __builtin_amdgcn_exp2f(-1.4426950408889634f * v0[e])); v1[e] = __builtin_amdgcn_rcpf(1.0f + __builtin_amdgcn_exp2f(-1.4426950408889634f * v1[e])); } }
;                     u32x4 w; w.x = cvt_pk_bf16(v0[0], v0[1]); w.y = cvt_pk_bf16(v0[2], v0[3]); w.z = cvt_pk_bf16(v1[0], v1[1]); w.w = cvt_pk_bf16(v1[2], v1[3]);
;                     *(u32x4*)(rowp + bj * HALF) = w; }
.LBB0_420:
	v_mov_b32_e32 v81, v80
	v_cvt_pk_bf16_f32 v88, v88, v89
	v_cvt_pk_bf16_f32 v89, v84, v85
	v_mov_b32_e32 v84, v80
	v_mov_b32_e32 v85, v80
	v_cvt_pk_bf16_f32 v90, v90, v91
	v_cvt_pk_bf16_f32 v91, v86, v87
	global_store_dwordx4 v[208:209], v[88:91], off
	v_pk_mul_f32 v[86:87], v[6:7], v[84:85]
	v_pk_mul_f32 v[84:85], v[2:3], v[84:85]
	v_pk_mul_f32 v[88:89], v[4:5], v[80:81]
	s_and_b64 vcc, exec, s[42:43]
	v_pk_mul_f32 v[80:81], v[0:1], v[80:81]
	s_cbranch_vccnz .LBB0_422
	v_max_f32_e32 v88, 0, v88
	v_max_f32_e32 v80, 0, v80
	v_max_f32_e32 v89, 0, v89
	v_max_f32_e32 v81, 0, v81
	v_max_f32_e32 v86, 0, v86
	v_max_f32_e32 v84, 0, v84
	v_max_f32_e32 v87, 0, v87
	v_max_f32_e32 v85, 0, v85
	v_pk_mul_f32 v[88:89], v[88:89], v[88:89]
	v_pk_mul_f32 v[86:87], v[86:87], v[86:87]
	v_pk_mul_f32 v[80:81], v[80:81], v[80:81]
	v_pk_mul_f32 v[84:85], v[84:85], v[84:85]

; __device__ __forceinline__ unsigned cvt_pk_bf16(float lo, float hi) { unsigned r; asm volatile("v_cvt_pk_bf16_f32 %0, %1, %2" : "=v"(r) : "v"(lo), "v"(hi)); return r; }
;     __device__ __forceinline__ void operator()(const f32x4 (&acc)[2][2][4][2], const Unit& u, int wr, int wc, int fr, int fq) const {
;     ...
;                     u32x4 w; w.x = cvt_pk_bf16(v0[0], v0[1]); w.y = cvt_pk_bf16(v0[2], v0[3]); w.z = cvt_pk_bf16(v1[0], v1[1]); w.w = cvt_pk_bf16(v1[2], v1[3]);
;                     *(u32x4*)(rowp + bj * HALF) = w; }
.LBB0_424:
	v_cvt_pk_bf16_f32 v88, v88, v89
	v_cvt_pk_bf16_f32 v89, v86, v87
	v_cvt_pk_bf16_f32 v90, v80, v81
	v_cvt_pk_bf16_f32 v91, v84, v85
	global_store_dwordx4 v[208:209], v[88:91], off offset:256
	s_branch .LBB0_359

; __device__ __forceinline__ unsigned cvt_pk_bf16(float lo, float hi) { unsigned r; asm volatile("v_cvt_pk_bf16_f32 %0, %1, %2" : "=v"(r) : "v"(lo), "v"(hi)); return r; }
;     __device__ __forceinline__ void operator()(const f32x4 (&acc)[2][2][4][2], const Unit& u, int wr, int wc, int fr, int fq) const {
;     ...
;             const int blk = colt >> 10, g = blk % 3, sec = blk / 3; const int dsh = (g == 0) ? 0 : (g == 1 ? 2 : 4); const int cin = (colt & 1023) + 64 * wc + 8 * fq;
;             f32x4 gn[2][2];
;             const float* gp = (sec == 0) ? qg + g * 64 : kg + g * 64;
; #pragma unroll
;             for (int bj = 0; bj < 2; ++bj)
; #pragma unroll
;                 for (int n = 0; n < 2; ++n) gn[bj][n] = (sec < 2) ? *(const f32x4*)(gp + 32 * bj + 8 * fq + 4 * n) : (f32x4){1.f, 1.f, 1.f, 1.f};
;             const float qsc = (sec == 0) ? 0.125f * 1.4426950408889634f : 1.0f;
; #pragma unroll
;             for (int ai = 0; ai < 2; ++ai)
; #pragma unroll
;                 for (int m = 0; m < 4; ++m) {
;                     const int r = row0 + ai * HALF + m * 16;
;                     const float rs = __builtin_amdgcn_rsqf((float)ss[r] * (1.0f / 1048576.0f) * (1.0f / 1024.0f) + EPS);
;                     f32x4 v[2][2]; float sq = 0.f;
; #pragma unroll
;                     for (int bj = 0; bj < 2; ++bj)
; #pragma unroll
;                         for (int n = 0; n < 2; ++n) { v[bj][n] = acc[ai][bj][m][n] * rs; sq += (v[bj][n][0] * v[bj][n][0] + v[bj][n][1] * v[bj][n][1]) + (v[bj][n][2] * v[bj][n][2] + v[bj][n][3] * v[bj][n][3]); }
;                     sq = x16_sum(sq); sq = x32_sum(sq);
;                     const float r2 = (sec < 2) ? qsc * __builtin_amdgcn_rsqf(sq * (1.0f / 64.0f) + EPS) : 1.0f;
;                     const int bl = r >> 13, t = r & 8191; const int pr = (bl << 13) + ((t & ((1 << dsh) - 1)) << (13 - dsh)) + (t >> dsh);
;                     bf16_t* rowp = O + (size_t)blk * SEC + (size_t)pr * 1024 + cin;
; #pragma unroll
;                     for (int bj = 0; bj < 2; ++bj) { const f32x4 v0 = v[bj][0] * gn[bj][0] * r2, v1 = v[bj][1] * gn[bj][1] * r2;
;                         u32x4 w; w.x = cvt_pk_bf16(v0[0], v0[1]); w.y = cvt_pk_bf16(v0[2], v0[3]); w.z = cvt_pk_bf16(v1[0], v1[1]); w.w = cvt_pk_bf16(v1[2], v1[3]);
;                         *(u32x4*)(rowp + bj * 32) = w; }
.LBB0_433:
	s_cmp_ge_u32 s88, 6
	s_cbranch_scc1 .Lv433
	s_mov_b32 vcc_lo, 0xff00ff00
	s_mov_b32 vcc_hi, 0xff00ff00
	s_nop 1
	v_lshl_add_u64 v[162:163], v[160:161], 3, s[48:49]
	s_cmp_eq_u32 s2, 1
	s_cselect_b32 s34, 2, 4
	s_cmp_lg_u32 s2, 0
	v_cndmask_b32_e64 v171, 1.0, v234, s[0:1]
	s_cselect_b32 s34, s34, 0
	s_sub_i32 s42, 13, s34
	s_and_b32 s43, s69, 0xffffe000
	s_ashr_i32 s89, s88, 31
	s_and_b32 s2, s76, 0x300
	s_lshl_b64 s[0:1], s[88:89], 25
	s_add_u32 s0, s28, s0
	v_or_b32_e32 v172, s2, v169
	s_addc_u32 s1, s29, s1
	s_movk_i32 s2, 0x1fdf
	s_mov_b32 s88, 0x1000
	s_cmp_eq_u32 s34, 0
	s_cselect_b32 s88, 0x4000, s88
	s_cmp_eq_u32 s34, 4
	s_cselect_b32 s88, 0x800000, s88
	s_lshr_b32 s89, 0x8000, s34
	v_mov_b32_e32 v220, s88
	v_mov_b32_e32 v176, s89
	s_mul_i32 s89, s89, 5
	v_mov_b32_e32 v177, 0
	v_sub_u32_e32 v218, 64, v220
	v_mov_b32_e32 v178, s89
	v_mov_b32_e32 v179, 0
	v_cndmask_b32_e64 v219, 0, -1, vcc
	v_cndmask_b32_e64 v218, 0, v218, vcc
	v_cndmask_b32_e64 v220, v220, 64, vcc
	v_mov_b32_e32 v221, 0
	s_waitcnt vmcnt(0)
	s_nop 1
	v_cvt_f32_u32_e32 v165, v193
	v_cvt_f32_u32_e32 v164, v192
	v_fmamk_f32 v164, v165, 0x4f800000, v164
	v_fmamk_f32 v164, v164, 0x30800000, v229
	v_rsq_f32_e32 v112, v164
	s_nop 0
	v_pk_mul_f32 v[144:145], v[144:145], v[112:113] op_sel_hi:[1,0]
	v_pk_mul_f32 v[222:223], v[144:145], v[144:145]
	v_pk_mul_f32 v[164:165], v[142:143], v[112:113] op_sel_hi:[1,0]
	v_pk_fma_f32 v[222:223], v[164:165], v[164:165], v[222:223]
	v_pk_mul_f32 v[140:141], v[140:141], v[112:113] op_sel_hi:[1,0]
	v_pk_fma_f32 v[222:223], v[140:141], v[140:141], v[222:223]
	v_pk_mul_f32 v[142:143], v[138:139], v[112:113] op_sel_hi:[1,0]
	v_pk_fma_f32 v[222:223], v[142:143], v[142:143], v[222:223]
	v_pk_mul_f32 v[136:137], v[136:137], v[112:113] op_sel_hi:[1,0]
	v_pk_fma_f32 v[222:223], v[136:137], v[136:137], v[222:223]
	v_pk_mul_f32 v[138:139], v[134:135], v[112:113] op_sel_hi:[1,0]
	v_pk_fma_f32 v[222:223], v[138:139], v[138:139], v[222:223]
	v_pk_mul_f32 v[132:133], v[132:133], v[112:113] op_sel_hi:[1,0]
	v_pk_fma_f32 v[222:223], v[132:133], v[132:133], v[222:223]
	v_pk_mul_f32 v[134:135], v[130:131], v[112:113] op_sel_hi:[1,0]
	v_pk_fma_f32 v[222:223], v[134:135], v[134:135], v[222:223]
	v_add_f32_e32 v112, v222, v223
	v_mov_b32_e32 v130, v112
	s_nop 1
	v_permlane16_swap_b32_e32 v112, v130
	v_add_f32_e32 v112, v112, v130
	v_mov_b32_e32 v130, v112
	s_nop 1
	v_permlane32_swap_b32_e32 v112, v130
	v_add_f32_e32 v112, v112, v130
	v_fmamk_f32 v112, v112, 0x3c800000, v229
	v_rsq_f32_e32 v112, v112
	v_lshlrev_b32_e32 v131, s42, v160
	v_and_b32_e32 v131, 0x1ffe, v131
	v_pk_mul_f32 v[164:165], v[92:93], v[164:165]
	v_mul_f32_e32 v112, v171, v112
	v_cndmask_b32_e64 v130, 1.0, v112, s[40:41]
	v_and_b32_e32 v112, 0x1fcf, v160
	v_lshrrev_b32_e32 v112, s34, v112
	v_or_b32_e32 v112, s43, v112
	v_add_u32_e32 v166, v112, v131
	v_ashrrev_i32_e32 v167, 31, v166
	v_lshlrev_b64 v[166:167], 11, v[166:167]
	v_lshl_add_u64 v[166:167], s[0:1], 0, v[166:167]
	v_lshlrev_b32_e32 v112, 1, v172
	v_pk_mul_f32 v[144:145], v[94:95], v[144:145]
	v_pk_mul_f32 v[142:143], v[88:89], v[142:143]
	v_pk_mul_f32 v[140:141], v[90:91], v[140:141]
	v_lshl_add_u64 v[166:167], v[166:167], 0, v[112:113]
	v_pk_mul_f32 v[144:145], v[144:145], v[130:131] op_sel_hi:[1,0]
	v_pk_mul_f32 v[164:165], v[164:165], v[130:131] op_sel_hi:[1,0]
	v_pk_mul_f32 v[172:173], v[140:141], v[130:131] op_sel_hi:[1,0]
	v_pk_mul_f32 v[142:143], v[142:143], v[130:131] op_sel_hi:[1,0]
	v_cvt_pk_bf16_f32 v184, v164, v165
	v_cvt_pk_bf16_f32 v185, v144, v145
	v_pk_mul_f32 v[134:135], v[80:81], v[134:135]
	v_pk_mul_f32 v[132:133], v[82:83], v[132:133]
	v_cvt_pk_bf16_f32 v186, v142, v143
	v_cvt_pk_bf16_f32 v187, v172, v173
	v_pk_mul_f32 v[138:139], v[84:85], v[138:139]
	v_pk_mul_f32 v[136:137], v[86:87], v[136:137]
	v_pk_mul_f32 v[140:141], v[132:133], v[130:131] op_sel_hi:[1,0]
	v_pk_mul_f32 v[132:133], v[134:135], v[130:131] op_sel_hi:[1,0]
	v_pk_mul_f32 v[136:137], v[136:137], v[130:131] op_sel_hi:[1,0]
	v_pk_mul_f32 v[138:139], v[138:139], v[130:131] op_sel_hi:[1,0]
	s_nop 0
	v_cvt_pk_bf16_f32 v130, v138, v139
	v_cvt_pk_bf16_f32 v131, v136, v137
	v_cvt_pk_bf16_f32 v132, v132, v133
	v_cvt_pk_bf16_f32 v133, v140, v141
	v_mov_b32_dpp v180, v184 row_ror:8 row_mask:0xf bank_mask:0xf
	v_mov_b32_dpp v181, v185 row_ror:8 row_mask:0xf bank_mask:0xf
	v_mov_b32_dpp v182, v186 row_ror:8 row_mask:0xf bank_mask:0xf
	v_mov_b32_dpp v183, v187 row_ror:8 row_mask:0xf bank_mask:0xf
	v_lshl_add_u64 v[212:213], v[166:167], 0, v[218:219]
	v_mov_b32_dpp v184, v130 row_ror:8 row_mask:0xf bank_mask:0xc
	v_mov_b32_dpp v185, v131 row_ror:8 row_mask:0xf bank_mask:0xc
	v_mov_b32_dpp v186, v132 row_ror:8 row_mask:0xf bank_mask:0xc
	v_mov_b32_dpp v187, v133 row_ror:8 row_mask:0xf bank_mask:0xc
	v_lshl_add_u64 v[214:215], v[166:167], 0, v[220:221]
	v_cndmask_b32_e32 v130, v180, v130, vcc
	v_cndmask_b32_e32 v131, v181, v131, vcc
	v_cndmask_b32_e32 v132, v182, v132, vcc
	v_cndmask_b32_e32 v133, v183, v133, vcc
	s_nop 0
	global_store_dwordx4 v[212:213], v[184:187], off
	global_store_dwordx4 v[214:215], v[130:133], off
	v_lshl_add_u64 v[174:175], v[166:167], 0, v[176:177]
	s_nop 1
	v_or_b32_e32 v133, 16, v160
	v_cvt_f32_u32_e32 v131, v195
	v_cvt_f32_u32_e32 v130, v194
	v_fmamk_f32 v130, v131, 0x4f800000, v130
	v_fmamk_f32 v130, v130, 0x30800000, v229
	v_rsq_f32_e32 v132, v130
	s_nop 0
	v_pk_mul_f32 v[128:129], v[128:129], v[132:133] op_sel_hi:[1,0]
	v_pk_mul_f32 v[222:223], v[128:129], v[128:129]
	v_pk_mul_f32 v[130:131], v[126:127], v[132:133] op_sel_hi:[1,0]
	v_pk_fma_f32 v[222:223], v[130:131], v[130:131], v[222:223]
; __device__ __forceinline__ unsigned cvt_pk_bf16(float lo, float hi) { unsigned r; asm volatile("v_cvt_pk_bf16_f32 %0, %1, %2" : "=v"(r) : "v"(lo), "v"(hi)); return r; }
; DI float x16_sum(float x) { const unsigned u = __builtin_bit_cast(unsigned, x); auto r = __builtin_amdgcn_permlane16_swap(u, u, false, false); return __builtin_bit_cast(float, (unsigned)r[0]) + __builtin_bit_cast(float, (unsigned)r[1]); }
; DI float x32_sum(float x) { const unsigned u = __builtin_bit_cast(unsigned, x); auto r = __builtin_amdgcn_permlane32_swap(u, u, false, false); return __builtin_bit_cast(float, (unsigned)r[0]) + __builtin_bit_cast(float, (unsigned)r[1]); }
;     __device__ __forceinline__ void operator()(const f32x4 (&acc)[2][2][4][2], const Unit& u, int wr, int wc, int fr, int fq) const {
;     ...
;                     const int r = row0 + ai * HALF + m * 16;
;                     const float rs = __builtin_amdgcn_rsqf((float)ss[r] * (1.0f / 1048576.0f) * (1.0f / 1024.0f) + EPS);
;                     f32x4 v[2][2]; float sq = 0.f;
; #pragma unroll
;                     for (int bj = 0; bj < 2; ++bj)
; #pragma unroll
;                         for (int n = 0; n < 2; ++n) { v[bj][n] = acc[ai][bj][m][n] * rs; sq += (v[bj][n][0] * v[bj][n][0] + v[bj][n][1] * v[bj][n][1]) + (v[bj][n][2] * v[bj][n][2] + v[bj][n][3] * v[bj][n][3]); }
;                     sq = x16_sum(sq); sq = x32_sum(sq);
;                     const float r2 = (sec < 2) ? qsc * __builtin_amdgcn_rsqf(sq * (1.0f / 64.0f) + EPS) : 1.0f;
;                     const int bl = r >> 13, t = r & 8191; const int pr = (bl << 13) + ((t & ((1 << dsh) - 1)) << (13 - dsh)) + (t >> dsh);
;                     bf16_t* rowp = O + (size_t)blk * SEC + (size_t)pr * 1024 + cin;
; #pragma unroll
;                     for (int bj = 0; bj < 2; ++bj) { const f32x4 v0 = v[bj][0] * gn[bj][0] * r2, v1 = v[bj][1] * gn[bj][1] * r2;
;                         u32x4 w; w.x = cvt_pk_bf16(v0[0], v0[1]); w.y = cvt_pk_bf16(v0[2], v0[3]); w.z = cvt_pk_bf16(v1[0], v1[1]); w.w = cvt_pk_bf16(v1[2], v1[3]);
;                         *(u32x4*)(rowp + bj * 32) = w; }
	v_pk_mul_f32 v[124:125], v[124:125], v[132:133] op_sel_hi:[1,0]
	v_pk_fma_f32 v[222:223], v[124:125], v[124:125], v[222:223]
	v_pk_mul_f32 v[126:127], v[122:123], v[132:133] op_sel_hi:[1,0]
	v_pk_fma_f32 v[222:223], v[126:127], v[126:127], v[222:223]
	v_pk_mul_f32 v[120:121], v[120:121], v[132:133] op_sel_hi:[1,0]
	v_pk_fma_f32 v[222:223], v[120:121], v[120:121], v[222:223]
	v_pk_mul_f32 v[122:123], v[118:119], v[132:133] op_sel_hi:[1,0]
	v_pk_fma_f32 v[222:223], v[122:123], v[122:123], v[222:223]
	v_pk_mul_f32 v[116:117], v[116:117], v[132:133] op_sel_hi:[1,0]
	v_pk_fma_f32 v[222:223], v[116:117], v[116:117], v[222:223]
	v_pk_mul_f32 v[118:119], v[114:115], v[132:133] op_sel_hi:[1,0]
	v_pk_fma_f32 v[222:223], v[118:119], v[118:119], v[222:223]
	v_add_f32_e32 v114, v222, v223
	v_mov_b32_e32 v115, v114
	s_nop 1
	v_permlane16_swap_b32_e32 v114, v115
	v_add_f32_e32 v114, v114, v115
	v_mov_b32_e32 v115, v114
	s_nop 1
	v_permlane32_swap_b32_e32 v114, v115
	v_add_f32_e32 v114, v114, v115
	v_fmamk_f32 v114, v114, 0x3c800000, v229
	v_rsq_f32_e32 v114, v114
	s_nop 0
	v_mul_f32_e32 v114, v171, v114
	v_cndmask_b32_e64 v114, 1.0, v114, s[40:41]
	v_pk_mul_f32 v[130:131], v[92:93], v[130:131]
	v_pk_mul_f32 v[128:129], v[94:95], v[128:129]
	v_pk_mul_f32 v[126:127], v[88:89], v[126:127]
	v_pk_mul_f32 v[124:125], v[90:91], v[124:125]
	v_pk_mul_f32 v[128:129], v[128:129], v[114:115] op_sel_hi:[1,0]
	v_pk_mul_f32 v[130:131], v[130:131], v[114:115] op_sel_hi:[1,0]
	v_pk_mul_f32 v[134:135], v[124:125], v[114:115] op_sel_hi:[1,0]
	v_pk_mul_f32 v[126:127], v[126:127], v[114:115] op_sel_hi:[1,0]
	v_cvt_pk_bf16_f32 v184, v130, v131
	v_cvt_pk_bf16_f32 v185, v128, v129
	v_pk_mul_f32 v[118:119], v[80:81], v[118:119]
	v_pk_mul_f32 v[116:117], v[82:83], v[116:117]
	v_cvt_pk_bf16_f32 v186, v126, v127
	v_cvt_pk_bf16_f32 v187, v134, v135
	v_pk_mul_f32 v[122:123], v[84:85], v[122:123]
	v_pk_mul_f32 v[120:121], v[86:87], v[120:121]
	v_pk_mul_f32 v[124:125], v[116:117], v[114:115] op_sel_hi:[1,0]
	v_pk_mul_f32 v[116:117], v[118:119], v[114:115] op_sel_hi:[1,0]
	v_pk_mul_f32 v[120:121], v[120:121], v[114:115] op_sel_hi:[1,0]
	v_pk_mul_f32 v[122:123], v[122:123], v[114:115] op_sel_hi:[1,0]
	s_movk_i32 s2, 0x1fef
	v_cvt_pk_bf16_f32 v114, v122, v123
	v_cvt_pk_bf16_f32 v115, v120, v121
	v_cvt_pk_bf16_f32 v116, v116, v117
	v_cvt_pk_bf16_f32 v117, v124, v125
	v_mov_b32_dpp v180, v184 row_ror:8 row_mask:0xf bank_mask:0xf
	v_mov_b32_dpp v181, v185 row_ror:8 row_mask:0xf bank_mask:0xf
	v_mov_b32_dpp v182, v186 row_ror:8 row_mask:0xf bank_mask:0xf
	v_mov_b32_dpp v183, v187 row_ror:8 row_mask:0xf bank_mask:0xf
	v_lshl_add_u64 v[212:213], v[174:175], 0, v[218:219]
	v_mov_b32_dpp v184, v114 row_ror:8 row_mask:0xf bank_mask:0xc
	v_mov_b32_dpp v185, v115 row_ror:8 row_mask:0xf bank_mask:0xc
	v_mov_b32_dpp v186, v116 row_ror:8 row_mask:0xf bank_mask:0xc
	v_mov_b32_dpp v187, v117 row_ror:8 row_mask:0xf bank_mask:0xc
	v_lshl_add_u64 v[214:215], v[174:175], 0, v[220:221]
	v_cndmask_b32_e32 v114, v180, v114, vcc
	v_cndmask_b32_e32 v115, v181, v115, vcc
	v_cndmask_b32_e32 v116, v182, v116, vcc
	v_cndmask_b32_e32 v117, v183, v117, vcc
	s_nop 0
	global_store_dwordx4 v[212:213], v[184:187], off
	global_store_dwordx4 v[214:215], v[114:117], off
	v_lshl_add_u64 v[174:175], v[174:175], 0, v[176:177]
	s_nop 1
	v_or_b32_e32 v117, 32, v160
	v_cvt_f32_u32_e32 v115, v197
	v_cvt_f32_u32_e32 v114, v196
	v_fmamk_f32 v114, v115, 0x4f800000, v114
	v_fmamk_f32 v114, v114, 0x30800000, v229
	v_rsq_f32_e32 v116, v114
	s_nop 0
	v_pk_mul_f32 v[110:111], v[110:111], v[116:117] op_sel_hi:[1,0]
	v_pk_mul_f32 v[222:223], v[110:111], v[110:111]
	v_pk_mul_f32 v[114:115], v[108:109], v[116:117] op_sel_hi:[1,0]
	v_pk_fma_f32 v[222:223], v[114:115], v[114:115], v[222:223]
	v_pk_mul_f32 v[106:107], v[106:107], v[116:117] op_sel_hi:[1,0]
	v_pk_fma_f32 v[222:223], v[106:107], v[106:107], v[222:223]
	v_pk_mul_f32 v[108:109], v[104:105], v[116:117] op_sel_hi:[1,0]
	v_pk_fma_f32 v[222:223], v[108:109], v[108:109], v[222:223]
	v_pk_mul_f32 v[102:103], v[102:103], v[116:117] op_sel_hi:[1,0]
	v_pk_fma_f32 v[222:223], v[102:103], v[102:103], v[222:223]
	v_pk_mul_f32 v[104:105], v[100:101], v[116:117] op_sel_hi:[1,0]
	v_pk_fma_f32 v[222:223], v[104:105], v[104:105], v[222:223]
	v_pk_mul_f32 v[98:99], v[98:99], v[116:117] op_sel_hi:[1,0]
	v_pk_fma_f32 v[222:223], v[98:99], v[98:99], v[222:223]
	v_pk_mul_f32 v[100:101], v[96:97], v[116:117] op_sel_hi:[1,0]
	v_pk_fma_f32 v[222:223], v[100:101], v[100:101], v[222:223]
	v_add_f32_e32 v96, v222, v223
	v_mov_b32_e32 v97, v96
	s_nop 1
	v_permlane16_swap_b32_e32 v96, v97
	v_add_f32_e32 v96, v96, v97
	v_mov_b32_e32 v97, v96
	s_nop 1
	v_permlane32_swap_b32_e32 v96, v97
	v_add_f32_e32 v96, v96, v97
	v_fmamk_f32 v96, v96, 0x3c800000, v229
	v_rsq_f32_e32 v96, v96
	s_nop 0
	v_mul_f32_e32 v96, v171, v96
	v_cndmask_b32_e64 v96, 1.0, v96, s[40:41]
	v_pk_mul_f32 v[114:115], v[92:93], v[114:115]
	v_pk_mul_f32 v[110:111], v[94:95], v[110:111]
	v_pk_mul_f32 v[108:109], v[88:89], v[108:109]
	v_pk_mul_f32 v[106:107], v[90:91], v[106:107]
	v_pk_mul_f32 v[110:111], v[110:111], v[96:97] op_sel_hi:[1,0]
	v_pk_mul_f32 v[114:115], v[114:115], v[96:97] op_sel_hi:[1,0]
	v_pk_mul_f32 v[118:119], v[106:107], v[96:97] op_sel_hi:[1,0]
	v_pk_mul_f32 v[108:109], v[108:109], v[96:97] op_sel_hi:[1,0]
	v_cvt_pk_bf16_f32 v184, v114, v115
	v_cvt_pk_bf16_f32 v185, v110, v111
	v_pk_mul_f32 v[100:101], v[80:81], v[100:101]
	v_pk_mul_f32 v[98:99], v[82:83], v[98:99]
	v_cvt_pk_bf16_f32 v186, v108, v109
	v_cvt_pk_bf16_f32 v187, v118, v119
	v_pk_mul_f32 v[104:105], v[84:85], v[104:105]
	v_pk_mul_f32 v[102:103], v[86:87], v[102:103]
; __device__ __forceinline__ unsigned cvt_pk_bf16(float lo, float hi) { unsigned r; asm volatile("v_cvt_pk_bf16_f32 %0, %1, %2" : "=v"(r) : "v"(lo), "v"(hi)); return r; }
; DI float x16_sum(float x) { const unsigned u = __builtin_bit_cast(unsigned, x); auto r = __builtin_amdgcn_permlane16_swap(u, u, false, false); return __builtin_bit_cast(float, (unsigned)r[0]) + __builtin_bit_cast(float, (unsigned)r[1]); }
; DI float x32_sum(float x) { const unsigned u = __builtin_bit_cast(unsigned, x); auto r = __builtin_amdgcn_permlane32_swap(u, u, false, false); return __builtin_bit_cast(float, (unsigned)r[0]) + __builtin_bit_cast(float, (unsigned)r[1]); }
;     __device__ __forceinline__ void operator()(const f32x4 (&acc)[2][2][4][2], const Unit& u, int wr, int wc, int fr, int fq) const {
;     ...
;                     const int r = row0 + ai * HALF + m * 16;
;                     const float rs = __builtin_amdgcn_rsqf((float)ss[r] * (1.0f / 1048576.0f) * (1.0f / 1024.0f) + EPS);
;                     f32x4 v[2][2]; float sq = 0.f;
; #pragma unroll
;                     for (int bj = 0; bj < 2; ++bj)
; #pragma unroll
;                         for (int n = 0; n < 2; ++n) { v[bj][n] = acc[ai][bj][m][n] * rs; sq += (v[bj][n][0] * v[bj][n][0] + v[bj][n][1] * v[bj][n][1]) + (v[bj][n][2] * v[bj][n][2] + v[bj][n][3] * v[bj][n][3]); }
;                     sq = x16_sum(sq); sq = x32_sum(sq);
;                     const float r2 = (sec < 2) ? qsc * __builtin_amdgcn_rsqf(sq * (1.0f / 64.0f) + EPS) : 1.0f;
;                     const int bl = r >> 13, t = r & 8191; const int pr = (bl << 13) + ((t & ((1 << dsh) - 1)) << (13 - dsh)) + (t >> dsh);
;                     bf16_t* rowp = O + (size_t)blk * SEC + (size_t)pr * 1024 + cin;
; #pragma unroll
;                     for (int bj = 0; bj < 2; ++bj) { const f32x4 v0 = v[bj][0] * gn[bj][0] * r2, v1 = v[bj][1] * gn[bj][1] * r2;
;                         u32x4 w; w.x = cvt_pk_bf16(v0[0], v0[1]); w.y = cvt_pk_bf16(v0[2], v0[3]); w.z = cvt_pk_bf16(v1[0], v1[1]); w.w = cvt_pk_bf16(v1[2], v1[3]);
;                         *(u32x4*)(rowp + bj * 32) = w; }
	v_pk_mul_f32 v[106:107], v[98:99], v[96:97] op_sel_hi:[1,0]
	v_pk_mul_f32 v[98:99], v[100:101], v[96:97] op_sel_hi:[1,0]
	v_pk_mul_f32 v[102:103], v[102:103], v[96:97] op_sel_hi:[1,0]
	v_pk_mul_f32 v[104:105], v[104:105], v[96:97] op_sel_hi:[1,0]
	s_movk_i32 s2, 0x1fff
	v_cvt_pk_bf16_f32 v96, v104, v105
	v_cvt_pk_bf16_f32 v97, v102, v103
	v_cvt_pk_bf16_f32 v98, v98, v99
	v_cvt_pk_bf16_f32 v99, v106, v107
	v_mov_b32_dpp v180, v184 row_ror:8 row_mask:0xf bank_mask:0xf
	v_mov_b32_dpp v181, v185 row_ror:8 row_mask:0xf bank_mask:0xf
	v_mov_b32_dpp v182, v186 row_ror:8 row_mask:0xf bank_mask:0xf
	v_mov_b32_dpp v183, v187 row_ror:8 row_mask:0xf bank_mask:0xf
	v_lshl_add_u64 v[212:213], v[174:175], 0, v[218:219]
	v_mov_b32_dpp v184, v96 row_ror:8 row_mask:0xf bank_mask:0xc
	v_mov_b32_dpp v185, v97 row_ror:8 row_mask:0xf bank_mask:0xc
	v_mov_b32_dpp v186, v98 row_ror:8 row_mask:0xf bank_mask:0xc
	v_mov_b32_dpp v187, v99 row_ror:8 row_mask:0xf bank_mask:0xc
	v_lshl_add_u64 v[214:215], v[174:175], 0, v[220:221]
	v_cndmask_b32_e32 v96, v180, v96, vcc
	v_cndmask_b32_e32 v97, v181, v97, vcc
	v_cndmask_b32_e32 v98, v182, v98, vcc
	v_cndmask_b32_e32 v99, v183, v99, vcc
	s_nop 0
	global_store_dwordx4 v[212:213], v[184:187], off
	global_store_dwordx4 v[214:215], v[96:99], off
	v_lshl_add_u64 v[174:175], v[174:175], 0, v[176:177]
	s_nop 1
	v_or_b32_e32 v99, 48, v160
	v_cvt_f32_u32_e32 v97, v199
	v_cvt_f32_u32_e32 v96, v198
	v_fmamk_f32 v96, v97, 0x4f800000, v96
	v_fmamk_f32 v96, v96, 0x30800000, v229
	v_rsq_f32_e32 v98, v96
	s_nop 0
	v_pk_mul_f32 v[78:79], v[78:79], v[98:99] op_sel_hi:[1,0]
	v_pk_mul_f32 v[222:223], v[78:79], v[78:79]
	v_pk_mul_f32 v[96:97], v[76:77], v[98:99] op_sel_hi:[1,0]
	v_pk_fma_f32 v[222:223], v[96:97], v[96:97], v[222:223]
	v_pk_mul_f32 v[74:75], v[74:75], v[98:99] op_sel_hi:[1,0]
	v_pk_fma_f32 v[222:223], v[74:75], v[74:75], v[222:223]
	v_pk_mul_f32 v[76:77], v[72:73], v[98:99] op_sel_hi:[1,0]
	v_pk_fma_f32 v[222:223], v[76:77], v[76:77], v[222:223]
	v_pk_mul_f32 v[70:71], v[70:71], v[98:99] op_sel_hi:[1,0]
	v_pk_fma_f32 v[222:223], v[70:71], v[70:71], v[222:223]
	v_pk_mul_f32 v[72:73], v[68:69], v[98:99] op_sel_hi:[1,0]
	v_pk_fma_f32 v[222:223], v[72:73], v[72:73], v[222:223]
	v_pk_mul_f32 v[66:67], v[66:67], v[98:99] op_sel_hi:[1,0]
	v_pk_fma_f32 v[222:223], v[66:67], v[66:67], v[222:223]
	v_pk_mul_f32 v[68:69], v[64:65], v[98:99] op_sel_hi:[1,0]
	v_pk_fma_f32 v[222:223], v[68:69], v[68:69], v[222:223]
	v_add_f32_e32 v64, v222, v223
	v_mov_b32_e32 v65, v64
	s_nop 1
	v_permlane16_swap_b32_e32 v64, v65
	v_add_f32_e32 v64, v64, v65
	v_mov_b32_e32 v65, v64
	s_nop 1
	v_permlane32_swap_b32_e32 v64, v65
	v_add_f32_e32 v64, v64, v65
	v_fmamk_f32 v64, v64, 0x3c800000, v229
	v_rsq_f32_e32 v64, v64
	s_nop 0
	v_mul_f32_e32 v64, v171, v64
	v_cndmask_b32_e64 v64, 1.0, v64, s[40:41]
	v_pk_mul_f32 v[96:97], v[92:93], v[96:97]
	v_pk_mul_f32 v[78:79], v[94:95], v[78:79]
	v_pk_mul_f32 v[76:77], v[88:89], v[76:77]
	v_pk_mul_f32 v[74:75], v[90:91], v[74:75]
	v_pk_mul_f32 v[78:79], v[78:79], v[64:65] op_sel_hi:[1,0]
	v_pk_mul_f32 v[96:97], v[96:97], v[64:65] op_sel_hi:[1,0]
	v_pk_mul_f32 v[100:101], v[74:75], v[64:65] op_sel_hi:[1,0]
	v_pk_mul_f32 v[76:77], v[76:77], v[64:65] op_sel_hi:[1,0]
	v_cvt_pk_bf16_f32 v184, v96, v97
	v_cvt_pk_bf16_f32 v185, v78, v79
	v_pk_mul_f32 v[68:69], v[80:81], v[68:69]
	v_pk_mul_f32 v[66:67], v[82:83], v[66:67]
	v_cvt_pk_bf16_f32 v186, v76, v77
	v_cvt_pk_bf16_f32 v187, v100, v101
	v_pk_mul_f32 v[72:73], v[84:85], v[72:73]
	v_pk_mul_f32 v[70:71], v[86:87], v[70:71]
	v_pk_mul_f32 v[74:75], v[66:67], v[64:65] op_sel_hi:[1,0]
	v_pk_mul_f32 v[66:67], v[68:69], v[64:65] op_sel_hi:[1,0]
	v_pk_mul_f32 v[70:71], v[70:71], v[64:65] op_sel_hi:[1,0]
	v_pk_mul_f32 v[72:73], v[72:73], v[64:65] op_sel_hi:[1,0]
	s_nop 0
	v_cvt_pk_bf16_f32 v64, v72, v73
	v_cvt_pk_bf16_f32 v65, v70, v71
	v_cvt_pk_bf16_f32 v66, v66, v67
	v_cvt_pk_bf16_f32 v67, v74, v75
	v_mov_b32_dpp v180, v184 row_ror:8 row_mask:0xf bank_mask:0xf
	v_mov_b32_dpp v181, v185 row_ror:8 row_mask:0xf bank_mask:0xf
	v_mov_b32_dpp v182, v186 row_ror:8 row_mask:0xf bank_mask:0xf
	v_mov_b32_dpp v183, v187 row_ror:8 row_mask:0xf bank_mask:0xf
	v_lshl_add_u64 v[212:213], v[174:175], 0, v[218:219]
	v_mov_b32_dpp v184, v64 row_ror:8 row_mask:0xf bank_mask:0xc
	v_mov_b32_dpp v185, v65 row_ror:8 row_mask:0xf bank_mask:0xc
	v_mov_b32_dpp v186, v66 row_ror:8 row_mask:0xf bank_mask:0xc
	v_mov_b32_dpp v187, v67 row_ror:8 row_mask:0xf bank_mask:0xc
	v_lshl_add_u64 v[214:215], v[174:175], 0, v[220:221]
	v_cndmask_b32_e32 v64, v180, v64, vcc
	v_cndmask_b32_e32 v65, v181, v65, vcc
	v_cndmask_b32_e32 v66, v182, v66, vcc
	v_cndmask_b32_e32 v67, v183, v67, vcc
	s_nop 0
	global_store_dwordx4 v[212:213], v[184:187], off
	global_store_dwordx4 v[214:215], v[64:67], off
	v_lshl_add_u64 v[174:175], v[174:175], 0, v[178:179]
	s_nop 1
	v_add_u32_e32 v67, 0x80, v160
	v_cvt_f32_u32_e32 v65, v201
	v_cvt_f32_u32_e32 v64, v200
	v_fmamk_f32 v64, v65, 0x4f800000, v64
	v_fmamk_f32 v64, v64, 0x30800000, v229
	v_rsq_f32_e32 v66, v64
	s_nop 0
	v_pk_mul_f32 v[62:63], v[62:63], v[66:67] op_sel_hi:[1,0]
	v_pk_mul_f32 v[222:223], v[62:63], v[62:63]
	v_pk_mul_f32 v[64:65], v[60:61], v[66:67] op_sel_hi:[1,0]
	v_pk_fma_f32 v[222:223], v[64:65], v[64:65], v[222:223]
	v_pk_mul_f32 v[58:59], v[58:59], v[66:67] op_sel_hi:[1,0]
	v_pk_fma_f32 v[222:223], v[58:59], v[58:59], v[222:223]
	v_pk_mul_f32 v[60:61], v[56:57], v[66:67] op_sel_hi:[1,0]
	v_pk_fma_f32 v[222:223], v[60:61], v[60:61], v[222:223]
	v_pk_mul_f32 v[54:55], v[54:55], v[66:67] op_sel_hi:[1,0]
	v_pk_fma_f32 v[222:223], v[54:55], v[54:55], v[222:223]
; __device__ __forceinline__ unsigned cvt_pk_bf16(float lo, float hi) { unsigned r; asm volatile("v_cvt_pk_bf16_f32 %0, %1, %2" : "=v"(r) : "v"(lo), "v"(hi)); return r; }
; DI float x16_sum(float x) { const unsigned u = __builtin_bit_cast(unsigned, x); auto r = __builtin_amdgcn_permlane16_swap(u, u, false, false); return __builtin_bit_cast(float, (unsigned)r[0]) + __builtin_bit_cast(float, (unsigned)r[1]); }
; DI float x32_sum(float x) { const unsigned u = __builtin_bit_cast(unsigned, x); auto r = __builtin_amdgcn_permlane32_swap(u, u, false, false); return __builtin_bit_cast(float, (unsigned)r[0]) + __builtin_bit_cast(float, (unsigned)r[1]); }
;     __device__ __forceinline__ void operator()(const f32x4 (&acc)[2][2][4][2], const Unit& u, int wr, int wc, int fr, int fq) const {
;     ...
;                     const int r = row0 + ai * HALF + m * 16;
;                     const float rs = __builtin_amdgcn_rsqf((float)ss[r] * (1.0f / 1048576.0f) * (1.0f / 1024.0f) + EPS);
;                     f32x4 v[2][2]; float sq = 0.f;
; #pragma unroll
;                     for (int bj = 0; bj < 2; ++bj)
; #pragma unroll
;                         for (int n = 0; n < 2; ++n) { v[bj][n] = acc[ai][bj][m][n] * rs; sq += (v[bj][n][0] * v[bj][n][0] + v[bj][n][1] * v[bj][n][1]) + (v[bj][n][2] * v[bj][n][2] + v[bj][n][3] * v[bj][n][3]); }
;                     sq = x16_sum(sq); sq = x32_sum(sq);
;                     const float r2 = (sec < 2) ? qsc * __builtin_amdgcn_rsqf(sq * (1.0f / 64.0f) + EPS) : 1.0f;
;                     const int bl = r >> 13, t = r & 8191; const int pr = (bl << 13) + ((t & ((1 << dsh) - 1)) << (13 - dsh)) + (t >> dsh);
;                     bf16_t* rowp = O + (size_t)blk * SEC + (size_t)pr * 1024 + cin;
; #pragma unroll
;                     for (int bj = 0; bj < 2; ++bj) { const f32x4 v0 = v[bj][0] * gn[bj][0] * r2, v1 = v[bj][1] * gn[bj][1] * r2;
;                         u32x4 w; w.x = cvt_pk_bf16(v0[0], v0[1]); w.y = cvt_pk_bf16(v0[2], v0[3]); w.z = cvt_pk_bf16(v1[0], v1[1]); w.w = cvt_pk_bf16(v1[2], v1[3]);
;                         *(u32x4*)(rowp + bj * 32) = w; }
	v_pk_mul_f32 v[56:57], v[52:53], v[66:67] op_sel_hi:[1,0]
	v_pk_fma_f32 v[222:223], v[56:57], v[56:57], v[222:223]
	v_pk_mul_f32 v[50:51], v[50:51], v[66:67] op_sel_hi:[1,0]
	v_pk_fma_f32 v[222:223], v[50:51], v[50:51], v[222:223]
	v_pk_mul_f32 v[52:53], v[48:49], v[66:67] op_sel_hi:[1,0]
	v_pk_fma_f32 v[222:223], v[52:53], v[52:53], v[222:223]
	v_add_f32_e32 v48, v222, v223
	v_mov_b32_e32 v49, v48
	s_nop 1
	v_permlane16_swap_b32_e32 v48, v49
	v_add_f32_e32 v48, v48, v49
	v_mov_b32_e32 v49, v48
	s_nop 1
	v_permlane32_swap_b32_e32 v48, v49
	v_add_f32_e32 v48, v48, v49
	v_fmamk_f32 v48, v48, 0x3c800000, v229
	v_rsq_f32_e32 v48, v48
	s_nop 0
	v_mul_f32_e32 v48, v171, v48
	v_cndmask_b32_e64 v48, 1.0, v48, s[40:41]
	v_pk_mul_f32 v[64:65], v[92:93], v[64:65]
	v_pk_mul_f32 v[62:63], v[94:95], v[62:63]
	v_pk_mul_f32 v[60:61], v[88:89], v[60:61]
	v_pk_mul_f32 v[58:59], v[90:91], v[58:59]
	v_pk_mul_f32 v[62:63], v[62:63], v[48:49] op_sel_hi:[1,0]
	v_pk_mul_f32 v[64:65], v[64:65], v[48:49] op_sel_hi:[1,0]
	v_pk_mul_f32 v[70:71], v[58:59], v[48:49] op_sel_hi:[1,0]
	v_pk_mul_f32 v[60:61], v[60:61], v[48:49] op_sel_hi:[1,0]
	v_cvt_pk_bf16_f32 v184, v64, v65
	v_cvt_pk_bf16_f32 v185, v62, v63
	v_pk_mul_f32 v[52:53], v[80:81], v[52:53]
	v_pk_mul_f32 v[50:51], v[82:83], v[50:51]
	v_cvt_pk_bf16_f32 v186, v60, v61
	v_cvt_pk_bf16_f32 v187, v70, v71
	v_pk_mul_f32 v[56:57], v[84:85], v[56:57]
	v_pk_mul_f32 v[54:55], v[86:87], v[54:55]
	v_pk_mul_f32 v[58:59], v[50:51], v[48:49] op_sel_hi:[1,0]
	v_pk_mul_f32 v[50:51], v[52:53], v[48:49] op_sel_hi:[1,0]
	v_pk_mul_f32 v[54:55], v[54:55], v[48:49] op_sel_hi:[1,0]
	v_pk_mul_f32 v[56:57], v[56:57], v[48:49] op_sel_hi:[1,0]
	s_nop 0
	v_cvt_pk_bf16_f32 v48, v56, v57
	v_cvt_pk_bf16_f32 v49, v54, v55
	v_cvt_pk_bf16_f32 v50, v50, v51
	v_cvt_pk_bf16_f32 v51, v58, v59
	v_mov_b32_dpp v180, v184 row_ror:8 row_mask:0xf bank_mask:0xf
	v_mov_b32_dpp v181, v185 row_ror:8 row_mask:0xf bank_mask:0xf
	v_mov_b32_dpp v182, v186 row_ror:8 row_mask:0xf bank_mask:0xf
	v_mov_b32_dpp v183, v187 row_ror:8 row_mask:0xf bank_mask:0xf
	v_lshl_add_u64 v[212:213], v[174:175], 0, v[218:219]
	v_mov_b32_dpp v184, v48 row_ror:8 row_mask:0xf bank_mask:0xc
	v_mov_b32_dpp v185, v49 row_ror:8 row_mask:0xf bank_mask:0xc
	v_mov_b32_dpp v186, v50 row_ror:8 row_mask:0xf bank_mask:0xc
	v_mov_b32_dpp v187, v51 row_ror:8 row_mask:0xf bank_mask:0xc
	v_lshl_add_u64 v[214:215], v[174:175], 0, v[220:221]
	v_cndmask_b32_e32 v48, v180, v48, vcc
	v_cndmask_b32_e32 v49, v181, v49, vcc
	v_cndmask_b32_e32 v50, v182, v50, vcc
	v_cndmask_b32_e32 v51, v183, v51, vcc
	s_nop 0
	global_store_dwordx4 v[212:213], v[184:187], off
	global_store_dwordx4 v[214:215], v[48:51], off
	v_lshl_add_u64 v[174:175], v[174:175], 0, v[176:177]
	s_nop 1
	v_add_u32_e32 v51, 0x90, v160
	v_cvt_f32_u32_e32 v49, v203
	v_cvt_f32_u32_e32 v48, v202
	v_fmamk_f32 v48, v49, 0x4f800000, v48
	v_fmamk_f32 v48, v48, 0x30800000, v229
	v_rsq_f32_e32 v50, v48
	s_nop 0
	v_pk_mul_f32 v[46:47], v[46:47], v[50:51] op_sel_hi:[1,0]
	v_pk_mul_f32 v[222:223], v[46:47], v[46:47]
	v_pk_mul_f32 v[48:49], v[44:45], v[50:51] op_sel_hi:[1,0]
	v_pk_fma_f32 v[222:223], v[48:49], v[48:49], v[222:223]
	v_pk_mul_f32 v[42:43], v[42:43], v[50:51] op_sel_hi:[1,0]
	v_pk_fma_f32 v[222:223], v[42:43], v[42:43], v[222:223]
	v_pk_mul_f32 v[44:45], v[40:41], v[50:51] op_sel_hi:[1,0]
	v_pk_fma_f32 v[222:223], v[44:45], v[44:45], v[222:223]
	v_pk_mul_f32 v[38:39], v[38:39], v[50:51] op_sel_hi:[1,0]
	v_pk_fma_f32 v[222:223], v[38:39], v[38:39], v[222:223]
	v_pk_mul_f32 v[40:41], v[36:37], v[50:51] op_sel_hi:[1,0]
	v_pk_fma_f32 v[222:223], v[40:41], v[40:41], v[222:223]
	v_pk_mul_f32 v[34:35], v[34:35], v[50:51] op_sel_hi:[1,0]
	v_pk_fma_f32 v[222:223], v[34:35], v[34:35], v[222:223]
	v_pk_mul_f32 v[36:37], v[32:33], v[50:51] op_sel_hi:[1,0]
	v_pk_fma_f32 v[222:223], v[36:37], v[36:37], v[222:223]
	v_add_f32_e32 v32, v222, v223
	v_mov_b32_e32 v33, v32
	s_nop 1
	v_permlane16_swap_b32_e32 v32, v33
	v_add_f32_e32 v32, v32, v33
	v_mov_b32_e32 v33, v32
	s_nop 1
	v_permlane32_swap_b32_e32 v32, v33
	v_add_f32_e32 v32, v32, v33
	v_fmamk_f32 v32, v32, 0x3c800000, v229
	v_rsq_f32_e32 v32, v32
	s_nop 0
	v_mul_f32_e32 v32, v171, v32
	v_cndmask_b32_e64 v32, 1.0, v32, s[40:41]
	v_pk_mul_f32 v[48:49], v[92:93], v[48:49]
	v_pk_mul_f32 v[46:47], v[94:95], v[46:47]
	v_pk_mul_f32 v[44:45], v[88:89], v[44:45]
	v_pk_mul_f32 v[42:43], v[90:91], v[42:43]
	v_pk_mul_f32 v[46:47], v[46:47], v[32:33] op_sel_hi:[1,0]
	v_pk_mul_f32 v[48:49], v[48:49], v[32:33] op_sel_hi:[1,0]
	v_pk_mul_f32 v[52:53], v[42:43], v[32:33] op_sel_hi:[1,0]
	v_pk_mul_f32 v[44:45], v[44:45], v[32:33] op_sel_hi:[1,0]
	v_cvt_pk_bf16_f32 v184, v48, v49
	v_cvt_pk_bf16_f32 v185, v46, v47
	v_pk_mul_f32 v[36:37], v[80:81], v[36:37]
	v_pk_mul_f32 v[34:35], v[82:83], v[34:35]
	v_cvt_pk_bf16_f32 v186, v44, v45
	v_cvt_pk_bf16_f32 v187, v52, v53
	v_pk_mul_f32 v[40:41], v[84:85], v[40:41]
	v_pk_mul_f32 v[38:39], v[86:87], v[38:39]
	v_pk_mul_f32 v[42:43], v[34:35], v[32:33] op_sel_hi:[1,0]
	v_pk_mul_f32 v[34:35], v[36:37], v[32:33] op_sel_hi:[1,0]
	v_pk_mul_f32 v[38:39], v[38:39], v[32:33] op_sel_hi:[1,0]
	v_pk_mul_f32 v[40:41], v[40:41], v[32:33] op_sel_hi:[1,0]
	s_nop 0
	v_cvt_pk_bf16_f32 v32, v40, v41
	v_cvt_pk_bf16_f32 v33, v38, v39
	v_cvt_pk_bf16_f32 v34, v34, v35
	v_cvt_pk_bf16_f32 v35, v42, v43
	v_mov_b32_dpp v180, v184 row_ror:8 row_mask:0xf bank_mask:0xf
	v_mov_b32_dpp v181, v185 row_ror:8 row_mask:0xf bank_mask:0xf
	v_mov_b32_dpp v182, v186 row_ror:8 row_mask:0xf bank_mask:0xf
	v_mov_b32_dpp v183, v187 row_ror:8 row_mask:0xf bank_mask:0xf
	v_lshl_add_u64 v[212:213], v[174:175], 0, v[218:219]
; __device__ __forceinline__ unsigned cvt_pk_bf16(float lo, float hi) { unsigned r; asm volatile("v_cvt_pk_bf16_f32 %0, %1, %2" : "=v"(r) : "v"(lo), "v"(hi)); return r; }
; DI float x16_sum(float x) { const unsigned u = __builtin_bit_cast(unsigned, x); auto r = __builtin_amdgcn_permlane16_swap(u, u, false, false); return __builtin_bit_cast(float, (unsigned)r[0]) + __builtin_bit_cast(float, (unsigned)r[1]); }
; DI float x32_sum(float x) { const unsigned u = __builtin_bit_cast(unsigned, x); auto r = __builtin_amdgcn_permlane32_swap(u, u, false, false); return __builtin_bit_cast(float, (unsigned)r[0]) + __builtin_bit_cast(float, (unsigned)r[1]); }
;     __device__ __forceinline__ void operator()(const f32x4 (&acc)[2][2][4][2], const Unit& u, int wr, int wc, int fr, int fq) const {
;     ...
;                     const int r = row0 + ai * HALF + m * 16;
;                     const float rs = __builtin_amdgcn_rsqf((float)ss[r] * (1.0f / 1048576.0f) * (1.0f / 1024.0f) + EPS);
;                     f32x4 v[2][2]; float sq = 0.f;
; #pragma unroll
;                     for (int bj = 0; bj < 2; ++bj)
; #pragma unroll
;                         for (int n = 0; n < 2; ++n) { v[bj][n] = acc[ai][bj][m][n] * rs; sq += (v[bj][n][0] * v[bj][n][0] + v[bj][n][1] * v[bj][n][1]) + (v[bj][n][2] * v[bj][n][2] + v[bj][n][3] * v[bj][n][3]); }
;                     sq = x16_sum(sq); sq = x32_sum(sq);
;                     const float r2 = (sec < 2) ? qsc * __builtin_amdgcn_rsqf(sq * (1.0f / 64.0f) + EPS) : 1.0f;
;                     const int bl = r >> 13, t = r & 8191; const int pr = (bl << 13) + ((t & ((1 << dsh) - 1)) << (13 - dsh)) + (t >> dsh);
;                     bf16_t* rowp = O + (size_t)blk * SEC + (size_t)pr * 1024 + cin;
; #pragma unroll
;                     for (int bj = 0; bj < 2; ++bj) { const f32x4 v0 = v[bj][0] * gn[bj][0] * r2, v1 = v[bj][1] * gn[bj][1] * r2;
;                         u32x4 w; w.x = cvt_pk_bf16(v0[0], v0[1]); w.y = cvt_pk_bf16(v0[2], v0[3]); w.z = cvt_pk_bf16(v1[0], v1[1]); w.w = cvt_pk_bf16(v1[2], v1[3]);
;                         *(u32x4*)(rowp + bj * 32) = w; }
	v_mov_b32_dpp v184, v32 row_ror:8 row_mask:0xf bank_mask:0xc
	v_mov_b32_dpp v185, v33 row_ror:8 row_mask:0xf bank_mask:0xc
	v_mov_b32_dpp v186, v34 row_ror:8 row_mask:0xf bank_mask:0xc
	v_mov_b32_dpp v187, v35 row_ror:8 row_mask:0xf bank_mask:0xc
	v_lshl_add_u64 v[214:215], v[174:175], 0, v[220:221]
	v_cndmask_b32_e32 v32, v180, v32, vcc
	v_cndmask_b32_e32 v33, v181, v33, vcc
	v_cndmask_b32_e32 v34, v182, v34, vcc
	v_cndmask_b32_e32 v35, v183, v35, vcc
	s_nop 0
	global_store_dwordx4 v[212:213], v[184:187], off
	global_store_dwordx4 v[214:215], v[32:35], off
	v_lshl_add_u64 v[174:175], v[174:175], 0, v[176:177]
	s_nop 1
	v_add_u32_e32 v35, 0xa0, v160
	v_cvt_f32_u32_e32 v33, v205
	v_cvt_f32_u32_e32 v32, v204
	v_fmamk_f32 v32, v33, 0x4f800000, v32
	v_fmamk_f32 v32, v32, 0x30800000, v229
	v_rsq_f32_e32 v34, v32
	s_nop 0
	v_pk_mul_f32 v[30:31], v[30:31], v[34:35] op_sel_hi:[1,0]
	v_pk_mul_f32 v[222:223], v[30:31], v[30:31]
	v_pk_mul_f32 v[32:33], v[28:29], v[34:35] op_sel_hi:[1,0]
	v_pk_fma_f32 v[222:223], v[32:33], v[32:33], v[222:223]
	v_pk_mul_f32 v[26:27], v[26:27], v[34:35] op_sel_hi:[1,0]
	v_pk_fma_f32 v[222:223], v[26:27], v[26:27], v[222:223]
	v_pk_mul_f32 v[28:29], v[24:25], v[34:35] op_sel_hi:[1,0]
	v_pk_fma_f32 v[222:223], v[28:29], v[28:29], v[222:223]
	v_pk_mul_f32 v[22:23], v[22:23], v[34:35] op_sel_hi:[1,0]
	v_pk_fma_f32 v[222:223], v[22:23], v[22:23], v[222:223]
	v_pk_mul_f32 v[24:25], v[20:21], v[34:35] op_sel_hi:[1,0]
	v_pk_fma_f32 v[222:223], v[24:25], v[24:25], v[222:223]
	v_pk_mul_f32 v[18:19], v[18:19], v[34:35] op_sel_hi:[1,0]
	v_pk_fma_f32 v[222:223], v[18:19], v[18:19], v[222:223]
	v_pk_mul_f32 v[20:21], v[16:17], v[34:35] op_sel_hi:[1,0]
	v_pk_fma_f32 v[222:223], v[20:21], v[20:21], v[222:223]
	v_add_f32_e32 v16, v222, v223
	v_mov_b32_e32 v17, v16
	s_nop 1
	v_permlane16_swap_b32_e32 v16, v17
	v_add_f32_e32 v16, v16, v17
	v_mov_b32_e32 v17, v16
	s_nop 1
	v_permlane32_swap_b32_e32 v16, v17
	v_add_f32_e32 v16, v16, v17
	v_fmamk_f32 v16, v16, 0x3c800000, v229
	v_rsq_f32_e32 v16, v16
	s_nop 0
	v_mul_f32_e32 v16, v171, v16
	v_cndmask_b32_e64 v16, 1.0, v16, s[40:41]
	v_pk_mul_f32 v[32:33], v[92:93], v[32:33]
	v_pk_mul_f32 v[30:31], v[94:95], v[30:31]
	v_pk_mul_f32 v[28:29], v[88:89], v[28:29]
	v_pk_mul_f32 v[26:27], v[90:91], v[26:27]
	v_pk_mul_f32 v[30:31], v[30:31], v[16:17] op_sel_hi:[1,0]
	v_pk_mul_f32 v[32:33], v[32:33], v[16:17] op_sel_hi:[1,0]
	v_pk_mul_f32 v[36:37], v[26:27], v[16:17] op_sel_hi:[1,0]
	v_pk_mul_f32 v[28:29], v[28:29], v[16:17] op_sel_hi:[1,0]
	v_cvt_pk_bf16_f32 v184, v32, v33
	v_cvt_pk_bf16_f32 v185, v30, v31
	v_pk_mul_f32 v[20:21], v[80:81], v[20:21]
	v_pk_mul_f32 v[18:19], v[82:83], v[18:19]
	v_cvt_pk_bf16_f32 v186, v28, v29
	v_cvt_pk_bf16_f32 v187, v36, v37
	v_pk_mul_f32 v[24:25], v[84:85], v[24:25]
	v_pk_mul_f32 v[22:23], v[86:87], v[22:23]
	v_pk_mul_f32 v[26:27], v[18:19], v[16:17] op_sel_hi:[1,0]
	v_pk_mul_f32 v[18:19], v[20:21], v[16:17] op_sel_hi:[1,0]
	v_pk_mul_f32 v[22:23], v[22:23], v[16:17] op_sel_hi:[1,0]
	v_pk_mul_f32 v[24:25], v[24:25], v[16:17] op_sel_hi:[1,0]
	s_nop 0
	v_cvt_pk_bf16_f32 v16, v24, v25
	v_cvt_pk_bf16_f32 v17, v22, v23
	v_cvt_pk_bf16_f32 v18, v18, v19
	v_cvt_pk_bf16_f32 v19, v26, v27
	v_mov_b32_dpp v180, v184 row_ror:8 row_mask:0xf bank_mask:0xf
	v_mov_b32_dpp v181, v185 row_ror:8 row_mask:0xf bank_mask:0xf
	v_mov_b32_dpp v182, v186 row_ror:8 row_mask:0xf bank_mask:0xf
	v_mov_b32_dpp v183, v187 row_ror:8 row_mask:0xf bank_mask:0xf
	v_lshl_add_u64 v[212:213], v[174:175], 0, v[218:219]
	v_mov_b32_dpp v184, v16 row_ror:8 row_mask:0xf bank_mask:0xc
	v_mov_b32_dpp v185, v17 row_ror:8 row_mask:0xf bank_mask:0xc
	v_mov_b32_dpp v186, v18 row_ror:8 row_mask:0xf bank_mask:0xc
	v_mov_b32_dpp v187, v19 row_ror:8 row_mask:0xf bank_mask:0xc
; __device__ __forceinline__ unsigned cvt_pk_bf16(float lo, float hi) { unsigned r; asm volatile("v_cvt_pk_bf16_f32 %0, %1, %2" : "=v"(r) : "v"(lo), "v"(hi)); return r; }
; DI float x16_sum(float x) { const unsigned u = __builtin_bit_cast(unsigned, x); auto r = __builtin_amdgcn_permlane16_swap(u, u, false, false); return __builtin_bit_cast(float, (unsigned)r[0]) + __builtin_bit_cast(float, (unsigned)r[1]); }
; DI float x32_sum(float x) { const unsigned u = __builtin_bit_cast(unsigned, x); auto r = __builtin_amdgcn_permlane32_swap(u, u, false, false); return __builtin_bit_cast(float, (unsigned)r[0]) + __builtin_bit_cast(float, (unsigned)r[1]); }
;     __device__ __forceinline__ void operator()(const f32x4 (&acc)[2][2][4][2], const Unit& u, int wr, int wc, int fr, int fq) const {
;     ...
;                     const int r = row0 + ai * HALF + m * 16;
;                     const float rs = __builtin_amdgcn_rsqf((float)ss[r] * (1.0f / 1048576.0f) * (1.0f / 1024.0f) + EPS);
;                     f32x4 v[2][2]; float sq = 0.f;
; #pragma unroll
;                     for (int bj = 0; bj < 2; ++bj)
; #pragma unroll
;                         for (int n = 0; n < 2; ++n) { v[bj][n] = acc[ai][bj][m][n] * rs; sq += (v[bj][n][0] * v[bj][n][0] + v[bj][n][1] * v[bj][n][1]) + (v[bj][n][2] * v[bj][n][2] + v[bj][n][3] * v[bj][n][3]); }
;                     sq = x16_sum(sq); sq = x32_sum(sq);
;                     const float r2 = (sec < 2) ? qsc * __builtin_amdgcn_rsqf(sq * (1.0f / 64.0f) + EPS) : 1.0f;
;                     const int bl = r >> 13, t = r & 8191; const int pr = (bl << 13) + ((t & ((1 << dsh) - 1)) << (13 - dsh)) + (t >> dsh);
;                     bf16_t* rowp = O + (size_t)blk * SEC + (size_t)pr * 1024 + cin;
; #pragma unroll
;                     for (int bj = 0; bj < 2; ++bj) { const f32x4 v0 = v[bj][0] * gn[bj][0] * r2, v1 = v[bj][1] * gn[bj][1] * r2;
;                         u32x4 w; w.x = cvt_pk_bf16(v0[0], v0[1]); w.y = cvt_pk_bf16(v0[2], v0[3]); w.z = cvt_pk_bf16(v1[0], v1[1]); w.w = cvt_pk_bf16(v1[2], v1[3]);
;                         *(u32x4*)(rowp + bj * 32) = w; }
	v_lshl_add_u64 v[214:215], v[174:175], 0, v[220:221]
	v_cndmask_b32_e32 v16, v180, v16, vcc
	v_cndmask_b32_e32 v17, v181, v17, vcc
	v_cndmask_b32_e32 v18, v182, v18, vcc
	v_cndmask_b32_e32 v19, v183, v19, vcc
	s_nop 0
	global_store_dwordx4 v[212:213], v[184:187], off
	global_store_dwordx4 v[214:215], v[16:19], off
	v_lshl_add_u64 v[174:175], v[174:175], 0, v[176:177]
	s_nop 1
	v_add_u32_e32 v19, 0xb0, v160
	v_cvt_f32_u32_e32 v17, v207
	v_cvt_f32_u32_e32 v16, v206
	v_fmamk_f32 v16, v17, 0x4f800000, v16
	v_fmamk_f32 v16, v16, 0x30800000, v229
	v_rsq_f32_e32 v18, v16
	s_nop 0
	v_pk_mul_f32 v[14:15], v[14:15], v[18:19] op_sel_hi:[1,0]
	v_pk_mul_f32 v[222:223], v[14:15], v[14:15]
	v_pk_mul_f32 v[16:17], v[12:13], v[18:19] op_sel_hi:[1,0]
	v_pk_fma_f32 v[222:223], v[16:17], v[16:17], v[222:223]
	v_pk_mul_f32 v[10:11], v[10:11], v[18:19] op_sel_hi:[1,0]
	v_pk_fma_f32 v[222:223], v[10:11], v[10:11], v[222:223]
	v_pk_mul_f32 v[12:13], v[8:9], v[18:19] op_sel_hi:[1,0]
	v_pk_fma_f32 v[222:223], v[12:13], v[12:13], v[222:223]
	v_pk_mul_f32 v[6:7], v[6:7], v[18:19] op_sel_hi:[1,0]
	v_pk_fma_f32 v[222:223], v[6:7], v[6:7], v[222:223]
	v_pk_mul_f32 v[8:9], v[4:5], v[18:19] op_sel_hi:[1,0]
	v_pk_fma_f32 v[222:223], v[8:9], v[8:9], v[222:223]
	v_pk_mul_f32 v[2:3], v[2:3], v[18:19] op_sel_hi:[1,0]
	v_pk_fma_f32 v[222:223], v[2:3], v[2:3], v[222:223]
	v_pk_mul_f32 v[4:5], v[0:1], v[18:19] op_sel_hi:[1,0]
	v_pk_fma_f32 v[222:223], v[4:5], v[4:5], v[222:223]
	v_add_f32_e32 v0, v222, v223
	v_mov_b32_e32 v1, v0
	s_nop 1
	v_permlane16_swap_b32_e32 v0, v1
	v_add_f32_e32 v0, v0, v1
	v_mov_b32_e32 v1, v0
	s_nop 1
	v_permlane32_swap_b32_e32 v0, v1
	v_add_f32_e32 v0, v0, v1
	v_fmamk_f32 v0, v0, 0x3c800000, v229
	v_rsq_f32_e32 v0, v0
	s_nop 0
	v_mul_f32_e32 v0, v171, v0
	v_cndmask_b32_e64 v0, 1.0, v0, s[40:41]
	v_pk_mul_f32 v[16:17], v[92:93], v[16:17]
	v_pk_mul_f32 v[14:15], v[94:95], v[14:15]
	v_pk_mul_f32 v[12:13], v[88:89], v[12:13]
	v_pk_mul_f32 v[10:11], v[90:91], v[10:11]
	v_pk_mul_f32 v[14:15], v[14:15], v[0:1] op_sel_hi:[1,0]
	v_pk_mul_f32 v[16:17], v[16:17], v[0:1] op_sel_hi:[1,0]
	v_pk_mul_f32 v[20:21], v[10:11], v[0:1] op_sel_hi:[1,0]
	v_pk_mul_f32 v[12:13], v[12:13], v[0:1] op_sel_hi:[1,0]
	v_cvt_pk_bf16_f32 v184, v16, v17
	v_cvt_pk_bf16_f32 v185, v14, v15
	v_pk_mul_f32 v[4:5], v[80:81], v[4:5]
	v_pk_mul_f32 v[2:3], v[82:83], v[2:3]
	v_cvt_pk_bf16_f32 v186, v12, v13
	v_cvt_pk_bf16_f32 v187, v20, v21
	v_pk_mul_f32 v[8:9], v[84:85], v[8:9]
	v_pk_mul_f32 v[6:7], v[86:87], v[6:7]
	v_pk_mul_f32 v[10:11], v[2:3], v[0:1] op_sel_hi:[1,0]
	v_pk_mul_f32 v[2:3], v[4:5], v[0:1] op_sel_hi:[1,0]
	v_pk_mul_f32 v[6:7], v[6:7], v[0:1] op_sel_hi:[1,0]
	v_pk_mul_f32 v[8:9], v[8:9], v[0:1] op_sel_hi:[1,0]
	s_nop 0
	v_cvt_pk_bf16_f32 v0, v8, v9
	v_cvt_pk_bf16_f32 v1, v6, v7
	v_cvt_pk_bf16_f32 v2, v2, v3
	v_cvt_pk_bf16_f32 v3, v10, v11
	v_mov_b32_dpp v180, v184 row_ror:8 row_mask:0xf bank_mask:0xf
	v_mov_b32_dpp v181, v185 row_ror:8 row_mask:0xf bank_mask:0xf
	v_mov_b32_dpp v182, v186 row_ror:8 row_mask:0xf bank_mask:0xf
	v_mov_b32_dpp v183, v187 row_ror:8 row_mask:0xf bank_mask:0xf
	v_lshl_add_u64 v[212:213], v[174:175], 0, v[218:219]
	v_mov_b32_dpp v184, v0 row_ror:8 row_mask:0xf bank_mask:0xc
	v_mov_b32_dpp v185, v1 row_ror:8 row_mask:0xf bank_mask:0xc
	v_mov_b32_dpp v186, v2 row_ror:8 row_mask:0xf bank_mask:0xc
	v_mov_b32_dpp v187, v3 row_ror:8 row_mask:0xf bank_mask:0xc
	v_lshl_add_u64 v[214:215], v[174:175], 0, v[220:221]
	v_cndmask_b32_e32 v0, v180, v0, vcc
	v_cndmask_b32_e32 v1, v181, v1, vcc
	v_cndmask_b32_e32 v2, v182, v2, vcc
	v_cndmask_b32_e32 v3, v183, v3, vcc
	s_nop 0
	global_store_dwordx4 v[212:213], v[184:187], off
	global_store_dwordx4 v[214:215], v[0:3], off
	s_andn2_b64 vcc, exec, s[38:39]
	s_mov_b64 s[0:1], -1
	s_cbranch_vccnz .LBB0_350

; __device__ __forceinline__ unsigned cvt_pk_bf16(float lo, float hi) { unsigned r; asm volatile("v_cvt_pk_bf16_f32 %0, %1, %2" : "=v"(r) : "v"(lo), "v"(hi)); return r; }
;     __device__ __forceinline__ void operator()(const f32x4 (&acc)[2][2][4][2], const Unit& u, int wr, int wc, int fr, int fq) const {
;     ...
;         if (mode == 0) {
;             const int blk = colt >> 10, g = blk % 3, sec = blk / 3; const int dsh = (g == 0) ? 0 : (g == 1 ? 2 : 4); const int cin = (colt & 1023) + 64 * wc + 8 * fq;
;             f32x4 gn[2][2];
;             const float* gp = (sec == 0) ? qg + g * 64 : kg + g * 64;
; #pragma unroll
;             for (int bj = 0; bj < 2; ++bj)
; #pragma unroll
;                 for (int n = 0; n < 2; ++n) gn[bj][n] = (sec < 2) ? *(const f32x4*)(gp + 32 * bj + 8 * fq + 4 * n) : (f32x4){1.f, 1.f, 1.f, 1.f};
;             const float qsc = (sec == 0) ? 0.125f * 1.4426950408889634f : 1.0f;
; #pragma unroll
;             for (int ai = 0; ai < 2; ++ai)
; #pragma unroll
;                 for (int m = 0; m < 4; ++m) {
;                     const int r = row0 + ai * HALF + m * 16;
;                     const float rs = __builtin_amdgcn_rsqf((float)ss[r] * (1.0f / 1048576.0f) * (1.0f / 1024.0f) + EPS);
;                     f32x4 v[2][2]; float sq = 0.f;
; #pragma unroll
;                     for (int bj = 0; bj < 2; ++bj)
; #pragma unroll
;                         for (int n = 0; n < 2; ++n) { v[bj][n] = acc[ai][bj][m][n] * rs; sq += (v[bj][n][0] * v[bj][n][0] + v[bj][n][1] * v[bj][n][1]) + (v[bj][n][2] * v[bj][n][2] + v[bj][n][3] * v[bj][n][3]); }
;                     sq = x16_sum(sq); sq = x32_sum(sq);
;                     const float r2 = (sec < 2) ? qsc * __builtin_amdgcn_rsqf(sq * (1.0f / 64.0f) + EPS) : 1.0f;
;                     const int bl = r >> 13, t = r & 8191; const int pr = (bl << 13) + ((t & ((1 << dsh) - 1)) << (13 - dsh)) + (t >> dsh);
;                     bf16_t* rowp = O + (size_t)blk * SEC + (size_t)pr * 1024 + cin;
; #pragma unroll
;                     for (int bj = 0; bj < 2; ++bj) { const f32x4 v0 = v[bj][0] * gn[bj][0] * r2, v1 = v[bj][1] * gn[bj][1] * r2;
;                         u32x4 w; w.x = cvt_pk_bf16(v0[0], v0[1]); w.y = cvt_pk_bf16(v0[2], v0[3]); w.z = cvt_pk_bf16(v1[0], v1[1]); w.w = cvt_pk_bf16(v1[2], v1[3]);
;                         *(u32x4*)(rowp + bj * 32) = w; }
.Lv433:
	s_mov_b32 vcc_lo, 0xff00ff00
	s_mov_b32 vcc_hi, 0xff00ff00
	s_nop 1
	v_lshl_add_u64 v[162:163], v[160:161], 3, s[48:49]
	s_cmp_eq_u32 s2, 1
	s_cselect_b32 s34, 2, 4
	s_cmp_lg_u32 s2, 0
	v_cndmask_b32_e64 v171, 1.0, v234, s[0:1]
	s_cselect_b32 s34, s34, 0
	s_sub_i32 s42, 13, s34
	s_and_b32 s43, s69, 0xffffe000
	s_ashr_i32 s89, s88, 31
	s_and_b32 s2, s76, 0x300
	s_lshl_b64 s[0:1], s[88:89], 25
	s_add_u32 s0, s28, s0
	v_or_b32_e32 v172, s2, v169
	s_addc_u32 s1, s29, s1
	s_movk_i32 s2, 0x1fdf
	s_mov_b32 s88, 0x1000
	s_cmp_eq_u32 s34, 0
	s_cselect_b32 s88, 0x4000, s88
	s_cmp_eq_u32 s34, 4
	s_cselect_b32 s88, 0x800000, s88
	s_lshr_b32 s89, 0x8000, s34
	v_mov_b32_e32 v220, s88
	v_mov_b32_e32 v176, s89
	s_mul_i32 s89, s89, 5
	v_mov_b32_e32 v177, 0
	v_sub_u32_e32 v218, 64, v220
	v_mov_b32_e32 v178, s89
	v_mov_b32_e32 v179, 0
	v_cndmask_b32_e64 v219, 0, -1, vcc
	v_cndmask_b32_e64 v218, 0, v218, vcc
	v_cndmask_b32_e64 v220, v220, 64, vcc
	v_mov_b32_e32 v221, 0
	s_waitcnt vmcnt(0)
	s_nop 1
	v_cvt_f32_u32_e32 v165, v193
	v_cvt_f32_u32_e32 v164, v192
	v_fmamk_f32 v164, v165, 0x4f800000, v164
	v_fmamk_f32 v164, v164, 0x30800000, v229
	v_rsq_f32_e32 v112, v164
	s_nop 0
	v_pk_mul_f32 v[144:145], v[144:145], v[112:113] op_sel_hi:[1,0]
	v_pk_mul_f32 v[164:165], v[142:143], v[112:113] op_sel_hi:[1,0]
	v_pk_mul_f32 v[140:141], v[140:141], v[112:113] op_sel_hi:[1,0]
	v_pk_mul_f32 v[142:143], v[138:139], v[112:113] op_sel_hi:[1,0]
	v_pk_mul_f32 v[136:137], v[136:137], v[112:113] op_sel_hi:[1,0]
	v_pk_mul_f32 v[138:139], v[134:135], v[112:113] op_sel_hi:[1,0]
	v_pk_mul_f32 v[132:133], v[132:133], v[112:113] op_sel_hi:[1,0]
	v_pk_mul_f32 v[134:135], v[130:131], v[112:113] op_sel_hi:[1,0]
	v_lshlrev_b32_e32 v131, s42, v160
	v_and_b32_e32 v131, 0x1ffe, v131
	v_and_b32_e32 v112, 0x1fcf, v160
	v_lshrrev_b32_e32 v112, s34, v112
	v_or_b32_e32 v112, s43, v112
	v_add_u32_e32 v166, v112, v131
	v_ashrrev_i32_e32 v167, 31, v166
	v_lshlrev_b64 v[166:167], 11, v[166:167]
	v_lshl_add_u64 v[166:167], s[0:1], 0, v[166:167]
	v_lshlrev_b32_e32 v112, 1, v172
	v_lshl_add_u64 v[166:167], v[166:167], 0, v[112:113]
	v_cvt_pk_bf16_f32 v184, v164, v165
	v_cvt_pk_bf16_f32 v185, v144, v145
	v_cvt_pk_bf16_f32 v186, v142, v143
	v_cvt_pk_bf16_f32 v187, v140, v141
	s_nop 0
	v_cvt_pk_bf16_f32 v208, v138, v139
	v_cvt_pk_bf16_f32 v209, v136, v137
	v_cvt_pk_bf16_f32 v210, v134, v135
	v_cvt_pk_bf16_f32 v211, v132, v133
	v_mov_b32_dpp v180, v184 row_ror:8 row_mask:0xf bank_mask:0xf
	v_mov_b32_dpp v181, v185 row_ror:8 row_mask:0xf bank_mask:0xf
	v_mov_b32_dpp v182, v186 row_ror:8 row_mask:0xf bank_mask:0xf
	v_mov_b32_dpp v183, v187 row_ror:8 row_mask:0xf bank_mask:0xf
	v_lshl_add_u64 v[212:213], v[166:167], 0, v[218:219]
	v_mov_b32_dpp v184, v208 row_ror:8 row_mask:0xf bank_mask:0xc
	v_mov_b32_dpp v185, v209 row_ror:8 row_mask:0xf bank_mask:0xc
	v_mov_b32_dpp v186, v210 row_ror:8 row_mask:0xf bank_mask:0xc
	v_mov_b32_dpp v187, v211 row_ror:8 row_mask:0xf bank_mask:0xc
	v_lshl_add_u64 v[214:215], v[166:167], 0, v[220:221]
	v_cndmask_b32_e32 v208, v180, v208, vcc
	v_cndmask_b32_e32 v209, v181, v209, vcc
	v_cndmask_b32_e32 v210, v182, v210, vcc
	v_cndmask_b32_e32 v211, v183, v211, vcc
	s_nop 0
	global_store_dwordx4 v[212:213], v[184:187], off
	global_store_dwordx4 v[214:215], v[208:211], off
	v_lshl_add_u64 v[174:175], v[166:167], 0, v[176:177]
	s_nop 1
	v_or_b32_e32 v133, 16, v160
	v_cvt_f32_u32_e32 v131, v195
	v_cvt_f32_u32_e32 v130, v194
	v_fmamk_f32 v130, v131, 0x4f800000, v130
	v_fmamk_f32 v130, v130, 0x30800000, v229
	v_rsq_f32_e32 v132, v130
	s_nop 0
	v_pk_mul_f32 v[128:129], v[128:129], v[132:133] op_sel_hi:[1,0]
	v_pk_mul_f32 v[130:131], v[126:127], v[132:133] op_sel_hi:[1,0]
	v_pk_mul_f32 v[124:125], v[124:125], v[132:133] op_sel_hi:[1,0]
	v_pk_mul_f32 v[126:127], v[122:123], v[132:133] op_sel_hi:[1,0]
	v_pk_mul_f32 v[120:121], v[120:121], v[132:133] op_sel_hi:[1,0]
	v_pk_mul_f32 v[122:123], v[118:119], v[132:133] op_sel_hi:[1,0]
	v_pk_mul_f32 v[116:117], v[116:117], v[132:133] op_sel_hi:[1,0]
	v_pk_mul_f32 v[118:119], v[114:115], v[132:133] op_sel_hi:[1,0]
	s_nop 0
	v_cvt_pk_bf16_f32 v184, v130, v131
	v_cvt_pk_bf16_f32 v185, v128, v129
	v_cvt_pk_bf16_f32 v186, v126, v127
	v_cvt_pk_bf16_f32 v187, v124, v125
	s_movk_i32 s2, 0x1fef
	v_cvt_pk_bf16_f32 v208, v122, v123
	v_cvt_pk_bf16_f32 v209, v120, v121
	v_cvt_pk_bf16_f32 v210, v118, v119
	v_cvt_pk_bf16_f32 v211, v116, v117
	v_mov_b32_dpp v180, v184 row_ror:8 row_mask:0xf bank_mask:0xf
	v_mov_b32_dpp v181, v185 row_ror:8 row_mask:0xf bank_mask:0xf
	v_mov_b32_dpp v182, v186 row_ror:8 row_mask:0xf bank_mask:0xf
	v_mov_b32_dpp v183, v187 row_ror:8 row_mask:0xf bank_mask:0xf
	v_lshl_add_u64 v[212:213], v[174:175], 0, v[218:219]
	v_mov_b32_dpp v184, v208 row_ror:8 row_mask:0xf bank_mask:0xc
	v_mov_b32_dpp v185, v209 row_ror:8 row_mask:0xf bank_mask:0xc
	v_mov_b32_dpp v186, v210 row_ror:8 row_mask:0xf bank_mask:0xc
	v_mov_b32_dpp v187, v211 row_ror:8 row_mask:0xf bank_mask:0xc
	v_lshl_add_u64 v[214:215], v[174:175], 0, v[220:221]
	v_cndmask_b32_e32 v208, v180, v208, vcc
	v_cndmask_b32_e32 v209, v181, v209, vcc
	v_cndmask_b32_e32 v210, v182, v210, vcc
	v_cndmask_b32_e32 v211, v183, v211, vcc
	s_nop 0
	global_store_dwordx4 v[212:213], v[184:187], off
	global_store_dwordx4 v[214:215], v[208:211], off
	v_lshl_add_u64 v[174:175], v[174:175], 0, v[176:177]
	s_nop 1
	v_or_b32_e32 v117, 32, v160
	v_cvt_f32_u32_e32 v115, v197
	v_cvt_f32_u32_e32 v114, v196
	v_fmamk_f32 v114, v115, 0x4f800000, v114
	v_fmamk_f32 v114, v114, 0x30800000, v229
	v_rsq_f32_e32 v116, v114
	s_nop 0
	v_pk_mul_f32 v[110:111], v[110:111], v[116:117] op_sel_hi:[1,0]
; __device__ __forceinline__ unsigned cvt_pk_bf16(float lo, float hi) { unsigned r; asm volatile("v_cvt_pk_bf16_f32 %0, %1, %2" : "=v"(r) : "v"(lo), "v"(hi)); return r; }
; DI float x16_sum(float x) { const unsigned u = __builtin_bit_cast(unsigned, x); auto r = __builtin_amdgcn_permlane16_swap(u, u, false, false); return __builtin_bit_cast(float, (unsigned)r[0]) + __builtin_bit_cast(float, (unsigned)r[1]); }
; DI float x32_sum(float x) { const unsigned u = __builtin_bit_cast(unsigned, x); auto r = __builtin_amdgcn_permlane32_swap(u, u, false, false); return __builtin_bit_cast(float, (unsigned)r[0]) + __builtin_bit_cast(float, (unsigned)r[1]); }
;     __device__ __forceinline__ void operator()(const f32x4 (&acc)[2][2][4][2], const Unit& u, int wr, int wc, int fr, int fq) const {
;     ...
;                     const int r = row0 + ai * HALF + m * 16;
;                     const float rs = __builtin_amdgcn_rsqf((float)ss[r] * (1.0f / 1048576.0f) * (1.0f / 1024.0f) + EPS);
;                     f32x4 v[2][2]; float sq = 0.f;
; #pragma unroll
;                     for (int bj = 0; bj < 2; ++bj)
; #pragma unroll
;                         for (int n = 0; n < 2; ++n) { v[bj][n] = acc[ai][bj][m][n] * rs; sq += (v[bj][n][0] * v[bj][n][0] + v[bj][n][1] * v[bj][n][1]) + (v[bj][n][2] * v[bj][n][2] + v[bj][n][3] * v[bj][n][3]); }
;                     sq = x16_sum(sq); sq = x32_sum(sq);
;                     const float r2 = (sec < 2) ? qsc * __builtin_amdgcn_rsqf(sq * (1.0f / 64.0f) + EPS) : 1.0f;
;                     const int bl = r >> 13, t = r & 8191; const int pr = (bl << 13) + ((t & ((1 << dsh) - 1)) << (13 - dsh)) + (t >> dsh);
;                     bf16_t* rowp = O + (size_t)blk * SEC + (size_t)pr * 1024 + cin;
; #pragma unroll
;                     for (int bj = 0; bj < 2; ++bj) { const f32x4 v0 = v[bj][0] * gn[bj][0] * r2, v1 = v[bj][1] * gn[bj][1] * r2;
;                         u32x4 w; w.x = cvt_pk_bf16(v0[0], v0[1]); w.y = cvt_pk_bf16(v0[2], v0[3]); w.z = cvt_pk_bf16(v1[0], v1[1]); w.w = cvt_pk_bf16(v1[2], v1[3]);
;                         *(u32x4*)(rowp + bj * 32) = w; }
	v_pk_mul_f32 v[114:115], v[108:109], v[116:117] op_sel_hi:[1,0]
	v_pk_mul_f32 v[106:107], v[106:107], v[116:117] op_sel_hi:[1,0]
	v_pk_mul_f32 v[108:109], v[104:105], v[116:117] op_sel_hi:[1,0]
	v_pk_mul_f32 v[102:103], v[102:103], v[116:117] op_sel_hi:[1,0]
	v_pk_mul_f32 v[104:105], v[100:101], v[116:117] op_sel_hi:[1,0]
	v_pk_mul_f32 v[98:99], v[98:99], v[116:117] op_sel_hi:[1,0]
	v_pk_mul_f32 v[100:101], v[96:97], v[116:117] op_sel_hi:[1,0]
	s_nop 0
	v_cvt_pk_bf16_f32 v184, v114, v115
	v_cvt_pk_bf16_f32 v185, v110, v111
	v_cvt_pk_bf16_f32 v186, v108, v109
	v_cvt_pk_bf16_f32 v187, v106, v107
	s_movk_i32 s2, 0x1fff
	v_cvt_pk_bf16_f32 v208, v104, v105
	v_cvt_pk_bf16_f32 v209, v102, v103
	v_cvt_pk_bf16_f32 v210, v100, v101
	v_cvt_pk_bf16_f32 v211, v98, v99
	v_mov_b32_dpp v180, v184 row_ror:8 row_mask:0xf bank_mask:0xf
	v_mov_b32_dpp v181, v185 row_ror:8 row_mask:0xf bank_mask:0xf
	v_mov_b32_dpp v182, v186 row_ror:8 row_mask:0xf bank_mask:0xf
	v_mov_b32_dpp v183, v187 row_ror:8 row_mask:0xf bank_mask:0xf
	v_lshl_add_u64 v[212:213], v[174:175], 0, v[218:219]
	v_mov_b32_dpp v184, v208 row_ror:8 row_mask:0xf bank_mask:0xc
	v_mov_b32_dpp v185, v209 row_ror:8 row_mask:0xf bank_mask:0xc
	v_mov_b32_dpp v186, v210 row_ror:8 row_mask:0xf bank_mask:0xc
	v_mov_b32_dpp v187, v211 row_ror:8 row_mask:0xf bank_mask:0xc
	v_lshl_add_u64 v[214:215], v[174:175], 0, v[220:221]
	v_cndmask_b32_e32 v208, v180, v208, vcc
	v_cndmask_b32_e32 v209, v181, v209, vcc
	v_cndmask_b32_e32 v210, v182, v210, vcc
	v_cndmask_b32_e32 v211, v183, v211, vcc
	s_nop 0
	global_store_dwordx4 v[212:213], v[184:187], off
	global_store_dwordx4 v[214:215], v[208:211], off
	v_lshl_add_u64 v[174:175], v[174:175], 0, v[176:177]
	s_nop 1
	v_or_b32_e32 v99, 48, v160
	v_cvt_f32_u32_e32 v97, v199
	v_cvt_f32_u32_e32 v96, v198
	v_fmamk_f32 v96, v97, 0x4f800000, v96
	v_fmamk_f32 v96, v96, 0x30800000, v229
	v_rsq_f32_e32 v98, v96
	s_nop 0
	v_pk_mul_f32 v[78:79], v[78:79], v[98:99] op_sel_hi:[1,0]
	v_pk_mul_f32 v[96:97], v[76:77], v[98:99] op_sel_hi:[1,0]
	v_pk_mul_f32 v[74:75], v[74:75], v[98:99] op_sel_hi:[1,0]
	v_pk_mul_f32 v[76:77], v[72:73], v[98:99] op_sel_hi:[1,0]
	v_pk_mul_f32 v[70:71], v[70:71], v[98:99] op_sel_hi:[1,0]
	v_pk_mul_f32 v[72:73], v[68:69], v[98:99] op_sel_hi:[1,0]
	v_pk_mul_f32 v[66:67], v[66:67], v[98:99] op_sel_hi:[1,0]
	v_pk_mul_f32 v[68:69], v[64:65], v[98:99] op_sel_hi:[1,0]
	s_nop 0
	v_cvt_pk_bf16_f32 v184, v96, v97
	v_cvt_pk_bf16_f32 v185, v78, v79
	v_cvt_pk_bf16_f32 v186, v76, v77
	v_cvt_pk_bf16_f32 v187, v74, v75
	s_nop 0
	v_cvt_pk_bf16_f32 v208, v72, v73
	v_cvt_pk_bf16_f32 v209, v70, v71
	v_cvt_pk_bf16_f32 v210, v68, v69
	v_cvt_pk_bf16_f32 v211, v66, v67
	v_mov_b32_dpp v180, v184 row_ror:8 row_mask:0xf bank_mask:0xf
	v_mov_b32_dpp v181, v185 row_ror:8 row_mask:0xf bank_mask:0xf
	v_mov_b32_dpp v182, v186 row_ror:8 row_mask:0xf bank_mask:0xf
	v_mov_b32_dpp v183, v187 row_ror:8 row_mask:0xf bank_mask:0xf
	v_lshl_add_u64 v[212:213], v[174:175], 0, v[218:219]
	v_mov_b32_dpp v184, v208 row_ror:8 row_mask:0xf bank_mask:0xc
	v_mov_b32_dpp v185, v209 row_ror:8 row_mask:0xf bank_mask:0xc
	v_mov_b32_dpp v186, v210 row_ror:8 row_mask:0xf bank_mask:0xc
	v_mov_b32_dpp v187, v211 row_ror:8 row_mask:0xf bank_mask:0xc
	v_lshl_add_u64 v[214:215], v[174:175], 0, v[220:221]
	v_cndmask_b32_e32 v208, v180, v208, vcc
	v_cndmask_b32_e32 v209, v181, v209, vcc
	v_cndmask_b32_e32 v210, v182, v210, vcc
	v_cndmask_b32_e32 v211, v183, v211, vcc
	s_nop 0
	global_store_dwordx4 v[212:213], v[184:187], off
	global_store_dwordx4 v[214:215], v[208:211], off
	v_lshl_add_u64 v[174:175], v[174:175], 0, v[178:179]
	s_nop 1
	v_add_u32_e32 v67, 0x80, v160
	v_cvt_f32_u32_e32 v65, v201
	v_cvt_f32_u32_e32 v64, v200
	v_fmamk_f32 v64, v65, 0x4f800000, v64
	v_fmamk_f32 v64, v64, 0x30800000, v229
	v_rsq_f32_e32 v66, v64
	s_nop 0
	v_pk_mul_f32 v[62:63], v[62:63], v[66:67] op_sel_hi:[1,0]
	v_pk_mul_f32 v[64:65], v[60:61], v[66:67] op_sel_hi:[1,0]
	v_pk_mul_f32 v[58:59], v[58:59], v[66:67] op_sel_hi:[1,0]
	v_pk_mul_f32 v[60:61], v[56:57], v[66:67] op_sel_hi:[1,0]
	v_pk_mul_f32 v[54:55], v[54:55], v[66:67] op_sel_hi:[1,0]
	v_pk_mul_f32 v[56:57], v[52:53], v[66:67] op_sel_hi:[1,0]
	v_pk_mul_f32 v[50:51], v[50:51], v[66:67] op_sel_hi:[1,0]
	v_pk_mul_f32 v[52:53], v[48:49], v[66:67] op_sel_hi:[1,0]
	s_nop 0
	v_cvt_pk_bf16_f32 v184, v64, v65
	v_cvt_pk_bf16_f32 v185, v62, v63
	v_cvt_pk_bf16_f32 v186, v60, v61
	v_cvt_pk_bf16_f32 v187, v58, v59
	s_nop 0
	v_cvt_pk_bf16_f32 v208, v56, v57
	v_cvt_pk_bf16_f32 v209, v54, v55
	v_cvt_pk_bf16_f32 v210, v52, v53
	v_cvt_pk_bf16_f32 v211, v50, v51
	v_mov_b32_dpp v180, v184 row_ror:8 row_mask:0xf bank_mask:0xf
	v_mov_b32_dpp v181, v185 row_ror:8 row_mask:0xf bank_mask:0xf
	v_mov_b32_dpp v182, v186 row_ror:8 row_mask:0xf bank_mask:0xf
	v_mov_b32_dpp v183, v187 row_ror:8 row_mask:0xf bank_mask:0xf
	v_lshl_add_u64 v[212:213], v[174:175], 0, v[218:219]
	v_mov_b32_dpp v184, v208 row_ror:8 row_mask:0xf bank_mask:0xc
	v_mov_b32_dpp v185, v209 row_ror:8 row_mask:0xf bank_mask:0xc
	v_mov_b32_dpp v186, v210 row_ror:8 row_mask:0xf bank_mask:0xc
	v_mov_b32_dpp v187, v211 row_ror:8 row_mask:0xf bank_mask:0xc
	v_lshl_add_u64 v[214:215], v[174:175], 0, v[220:221]
	v_cndmask_b32_e32 v208, v180, v208, vcc
	v_cndmask_b32_e32 v209, v181, v209, vcc
	v_cndmask_b32_e32 v210, v182, v210, vcc
	v_cndmask_b32_e32 v211, v183, v211, vcc
	s_nop 0
	global_store_dwordx4 v[212:213], v[184:187], off
	global_store_dwordx4 v[214:215], v[208:211], off
	v_lshl_add_u64 v[174:175], v[174:175], 0, v[176:177]
	s_nop 1
	v_add_u32_e32 v51, 0x90, v160
	v_cvt_f32_u32_e32 v49, v203
	v_cvt_f32_u32_e32 v48, v202
; __device__ __forceinline__ unsigned cvt_pk_bf16(float lo, float hi) { unsigned r; asm volatile("v_cvt_pk_bf16_f32 %0, %1, %2" : "=v"(r) : "v"(lo), "v"(hi)); return r; }
; DI float x16_sum(float x) { const unsigned u = __builtin_bit_cast(unsigned, x); auto r = __builtin_amdgcn_permlane16_swap(u, u, false, false); return __builtin_bit_cast(float, (unsigned)r[0]) + __builtin_bit_cast(float, (unsigned)r[1]); }
; DI float x32_sum(float x) { const unsigned u = __builtin_bit_cast(unsigned, x); auto r = __builtin_amdgcn_permlane32_swap(u, u, false, false); return __builtin_bit_cast(float, (unsigned)r[0]) + __builtin_bit_cast(float, (unsigned)r[1]); }
;     __device__ __forceinline__ void operator()(const f32x4 (&acc)[2][2][4][2], const Unit& u, int wr, int wc, int fr, int fq) const {
;     ...
;                     const int r = row0 + ai * HALF + m * 16;
;                     const float rs = __builtin_amdgcn_rsqf((float)ss[r] * (1.0f / 1048576.0f) * (1.0f / 1024.0f) + EPS);
;                     f32x4 v[2][2]; float sq = 0.f;
; #pragma unroll
;                     for (int bj = 0; bj < 2; ++bj)
; #pragma unroll
;                         for (int n = 0; n < 2; ++n) { v[bj][n] = acc[ai][bj][m][n] * rs; sq += (v[bj][n][0] * v[bj][n][0] + v[bj][n][1] * v[bj][n][1]) + (v[bj][n][2] * v[bj][n][2] + v[bj][n][3] * v[bj][n][3]); }
;                     sq = x16_sum(sq); sq = x32_sum(sq);
;                     const float r2 = (sec < 2) ? qsc * __builtin_amdgcn_rsqf(sq * (1.0f / 64.0f) + EPS) : 1.0f;
;                     const int bl = r >> 13, t = r & 8191; const int pr = (bl << 13) + ((t & ((1 << dsh) - 1)) << (13 - dsh)) + (t >> dsh);
;                     bf16_t* rowp = O + (size_t)blk * SEC + (size_t)pr * 1024 + cin;
; #pragma unroll
;                     for (int bj = 0; bj < 2; ++bj) { const f32x4 v0 = v[bj][0] * gn[bj][0] * r2, v1 = v[bj][1] * gn[bj][1] * r2;
;                         u32x4 w; w.x = cvt_pk_bf16(v0[0], v0[1]); w.y = cvt_pk_bf16(v0[2], v0[3]); w.z = cvt_pk_bf16(v1[0], v1[1]); w.w = cvt_pk_bf16(v1[2], v1[3]);
;                         *(u32x4*)(rowp + bj * 32) = w; }
	v_fmamk_f32 v48, v49, 0x4f800000, v48
	v_fmamk_f32 v48, v48, 0x30800000, v229
	v_rsq_f32_e32 v50, v48
	s_nop 0
	v_pk_mul_f32 v[46:47], v[46:47], v[50:51] op_sel_hi:[1,0]
	v_pk_mul_f32 v[48:49], v[44:45], v[50:51] op_sel_hi:[1,0]
	v_pk_mul_f32 v[42:43], v[42:43], v[50:51] op_sel_hi:[1,0]
	v_pk_mul_f32 v[44:45], v[40:41], v[50:51] op_sel_hi:[1,0]
	v_pk_mul_f32 v[38:39], v[38:39], v[50:51] op_sel_hi:[1,0]
	v_pk_mul_f32 v[40:41], v[36:37], v[50:51] op_sel_hi:[1,0]
	v_pk_mul_f32 v[34:35], v[34:35], v[50:51] op_sel_hi:[1,0]
	v_pk_mul_f32 v[36:37], v[32:33], v[50:51] op_sel_hi:[1,0]
	s_nop 0
	v_cvt_pk_bf16_f32 v184, v48, v49
	v_cvt_pk_bf16_f32 v185, v46, v47
	v_cvt_pk_bf16_f32 v186, v44, v45
	v_cvt_pk_bf16_f32 v187, v42, v43
	s_nop 0
	v_cvt_pk_bf16_f32 v208, v40, v41
	v_cvt_pk_bf16_f32 v209, v38, v39
	v_cvt_pk_bf16_f32 v210, v36, v37
	v_cvt_pk_bf16_f32 v211, v34, v35
	v_mov_b32_dpp v180, v184 row_ror:8 row_mask:0xf bank_mask:0xf
	v_mov_b32_dpp v181, v185 row_ror:8 row_mask:0xf bank_mask:0xf
	v_mov_b32_dpp v182, v186 row_ror:8 row_mask:0xf bank_mask:0xf
	v_mov_b32_dpp v183, v187 row_ror:8 row_mask:0xf bank_mask:0xf
	v_lshl_add_u64 v[212:213], v[174:175], 0, v[218:219]
	v_mov_b32_dpp v184, v208 row_ror:8 row_mask:0xf bank_mask:0xc
	v_mov_b32_dpp v185, v209 row_ror:8 row_mask:0xf bank_mask:0xc
	v_mov_b32_dpp v186, v210 row_ror:8 row_mask:0xf bank_mask:0xc
	v_mov_b32_dpp v187, v211 row_ror:8 row_mask:0xf bank_mask:0xc
	v_lshl_add_u64 v[214:215], v[174:175], 0, v[220:221]
	v_cndmask_b32_e32 v208, v180, v208, vcc
	v_cndmask_b32_e32 v209, v181, v209, vcc
	v_cndmask_b32_e32 v210, v182, v210, vcc
	v_cndmask_b32_e32 v211, v183, v211, vcc
	s_nop 0
	global_store_dwordx4 v[212:213], v[184:187], off
	global_store_dwordx4 v[214:215], v[208:211], off
	v_lshl_add_u64 v[174:175], v[174:175], 0, v[176:177]
	s_nop 1
	v_add_u32_e32 v35, 0xa0, v160
	v_cvt_f32_u32_e32 v33, v205
	v_cvt_f32_u32_e32 v32, v204
	v_fmamk_f32 v32, v33, 0x4f800000, v32
	v_fmamk_f32 v32, v32, 0x30800000, v229
	v_rsq_f32_e32 v34, v32
	s_nop 0
	v_pk_mul_f32 v[30:31], v[30:31], v[34:35] op_sel_hi:[1,0]
	v_pk_mul_f32 v[32:33], v[28:29], v[34:35] op_sel_hi:[1,0]
	v_pk_mul_f32 v[26:27], v[26:27], v[34:35] op_sel_hi:[1,0]
	v_pk_mul_f32 v[28:29], v[24:25], v[34:35] op_sel_hi:[1,0]
	v_pk_mul_f32 v[22:23], v[22:23], v[34:35] op_sel_hi:[1,0]
	v_pk_mul_f32 v[24:25], v[20:21], v[34:35] op_sel_hi:[1,0]
	v_pk_mul_f32 v[18:19], v[18:19], v[34:35] op_sel_hi:[1,0]
	v_pk_mul_f32 v[20:21], v[16:17], v[34:35] op_sel_hi:[1,0]
	s_nop 0
	v_cvt_pk_bf16_f32 v184, v32, v33
	v_cvt_pk_bf16_f32 v185, v30, v31
	v_cvt_pk_bf16_f32 v186, v28, v29
	v_cvt_pk_bf16_f32 v187, v26, v27
	s_nop 0
	v_cvt_pk_bf16_f32 v208, v24, v25
	v_cvt_pk_bf16_f32 v209, v22, v23
	v_cvt_pk_bf16_f32 v210, v20, v21
	v_cvt_pk_bf16_f32 v211, v18, v19
	v_mov_b32_dpp v180, v184 row_ror:8 row_mask:0xf bank_mask:0xf
	v_mov_b32_dpp v181, v185 row_ror:8 row_mask:0xf bank_mask:0xf
	v_mov_b32_dpp v182, v186 row_ror:8 row_mask:0xf bank_mask:0xf
	v_mov_b32_dpp v183, v187 row_ror:8 row_mask:0xf bank_mask:0xf
	v_lshl_add_u64 v[212:213], v[174:175], 0, v[218:219]
	v_mov_b32_dpp v184, v208 row_ror:8 row_mask:0xf bank_mask:0xc
	v_mov_b32_dpp v185, v209 row_ror:8 row_mask:0xf bank_mask:0xc
	v_mov_b32_dpp v186, v210 row_ror:8 row_mask:0xf bank_mask:0xc
	v_mov_b32_dpp v187, v211 row_ror:8 row_mask:0xf bank_mask:0xc
	v_lshl_add_u64 v[214:215], v[174:175], 0, v[220:221]
	v_cndmask_b32_e32 v208, v180, v208, vcc
	v_cndmask_b32_e32 v209, v181, v209, vcc
	v_cndmask_b32_e32 v210, v182, v210, vcc
	v_cndmask_b32_e32 v211, v183, v211, vcc
	s_nop 0
	global_store_dwordx4 v[212:213], v[184:187], off
	global_store_dwordx4 v[214:215], v[208:211], off
	v_lshl_add_u64 v[174:175], v[174:175], 0, v[176:177]
	s_nop 1
	v_add_u32_e32 v19, 0xb0, v160
	v_cvt_f32_u32_e32 v17, v207
	v_cvt_f32_u32_e32 v16, v206
	v_fmamk_f32 v16, v17, 0x4f800000, v16
	v_fmamk_f32 v16, v16, 0x30800000, v229
	v_rsq_f32_e32 v18, v16
	s_nop 0
	v_pk_mul_f32 v[14:15], v[14:15], v[18:19] op_sel_hi:[1,0]
	v_pk_mul_f32 v[16:17], v[12:13], v[18:19] op_sel_hi:[1,0]
	v_pk_mul_f32 v[10:11], v[10:11], v[18:19] op_sel_hi:[1,0]
	v_pk_mul_f32 v[12:13], v[8:9], v[18:19] op_sel_hi:[1,0]
	v_pk_mul_f32 v[6:7], v[6:7], v[18:19] op_sel_hi:[1,0]
	v_pk_mul_f32 v[8:9], v[4:5], v[18:19] op_sel_hi:[1,0]
	v_pk_mul_f32 v[2:3], v[2:3], v[18:19] op_sel_hi:[1,0]
	v_pk_mul_f32 v[4:5], v[0:1], v[18:19] op_sel_hi:[1,0]
	s_nop 0
	v_cvt_pk_bf16_f32 v184, v16, v17
	v_cvt_pk_bf16_f32 v185, v14, v15
	v_cvt_pk_bf16_f32 v186, v12, v13
	v_cvt_pk_bf16_f32 v187, v10, v11
	s_nop 0
	v_cvt_pk_bf16_f32 v208, v8, v9
	v_cvt_pk_bf16_f32 v209, v6, v7
	v_cvt_pk_bf16_f32 v210, v4, v5
	v_cvt_pk_bf16_f32 v211, v2, v3
	v_mov_b32_dpp v180, v184 row_ror:8 row_mask:0xf bank_mask:0xf
	v_mov_b32_dpp v181, v185 row_ror:8 row_mask:0xf bank_mask:0xf
	v_mov_b32_dpp v182, v186 row_ror:8 row_mask:0xf bank_mask:0xf
	v_mov_b32_dpp v183, v187 row_ror:8 row_mask:0xf bank_mask:0xf
	v_lshl_add_u64 v[212:213], v[174:175], 0, v[218:219]
	v_mov_b32_dpp v184, v208 row_ror:8 row_mask:0xf bank_mask:0xc
	v_mov_b32_dpp v185, v209 row_ror:8 row_mask:0xf bank_mask:0xc
	v_mov_b32_dpp v186, v210 row_ror:8 row_mask:0xf bank_mask:0xc
	v_mov_b32_dpp v187, v211 row_ror:8 row_mask:0xf bank_mask:0xc
	v_lshl_add_u64 v[214:215], v[174:175], 0, v[220:221]
	v_cndmask_b32_e32 v208, v180, v208, vcc
	v_cndmask_b32_e32 v209, v181, v209, vcc
	v_cndmask_b32_e32 v210, v182, v210, vcc
	v_cndmask_b32_e32 v211, v183, v211, vcc
	s_nop 0
	global_store_dwordx4 v[212:213], v[184:187], off
	global_store_dwordx4 v[214:215], v[208:211], off
	s_andn2_b64 vcc, exec, s[38:39]
	s_mov_b64 s[0:1], -1
	s_cbranch_vccnz .LBB0_350
	s_branch .LBB0_434
